# FFN-up epilogue: 256 dead zero-initialisations before full-row DPP rotates removed
# baseline (speedup 1.0000x reference)
.LBB0_1609:
	s_add_u32 s44, s42, 0xfffc0080
	s_addc_u32 s45, s43, -1
	s_add_i32 s49, 0, 0x10000
	v_add_u32_e32 v116, s49, v238
	ds_read_b128 v[104:107], v116
	ds_read_b128 v[108:111], v116 offset:1024
	ds_read_b128 v[112:115], v116 offset:2048
	ds_read_b128 v[116:119], v116 offset:3072
	s_cmp_eq_u32 s23, 12
	s_cselect_b32 s47, s37, s45
	s_cselect_b32 s46, s36, s44
	s_cselect_b32 s45, s39, s19
	s_cselect_b32 s44, s38, s3
	v_lshl_add_u64 v[198:199], s[42:43], 0, v[164:165]
	s_add_i32 m0, s54, 0xc000
	ds_read_b128 v[120:123], v239
	ds_read_b128 v[124:127], v239 offset:1024
	ds_read_b128 v[128:131], v239 offset:2048
	ds_read_b128 v[132:135], v239 offset:3072
	ds_read_b128 v[168:171], v239 offset:4096
	ds_read_b128 v[172:175], v239 offset:5120
	ds_read_b128 v[190:193], v239 offset:6144
	ds_read_b128 v[194:197], v239 offset:7168
	global_load_lds_dwordx4 v[198:199], off
	v_lshl_add_u64 v[198:199], s[42:43], 0, v[166:167]
	s_add_i32 m0, s54, 0xe000
	s_nop 0
	global_load_lds_dwordx4 v[198:199], off
	s_waitcnt lgkmcnt(8)
	s_barrier
	s_waitcnt lgkmcnt(0)
	s_setprio 1
	s_waitcnt lgkmcnt(0)
	v_mfma_f32_16x16x32_bf16 v[156:159], v[104:107], v[120:123], v[156:159]
	v_mfma_f32_16x16x32_bf16 v[60:63], v[112:115], v[120:123], v[60:63]
	v_mfma_f32_16x16x32_bf16 v[148:151], v[104:107], v[128:131], v[148:151]
	v_mfma_f32_16x16x32_bf16 v[52:55], v[112:115], v[128:131], v[52:55]
	v_mfma_f32_16x16x32_bf16 v[140:143], v[104:107], v[168:171], v[140:143]
	v_mfma_f32_16x16x32_bf16 v[44:47], v[112:115], v[168:171], v[44:47]
	v_mfma_f32_16x16x32_bf16 v[100:103], v[104:107], v[190:193], v[100:103]
	v_mfma_f32_16x16x32_bf16 v[36:39], v[112:115], v[190:193], v[36:39]
	v_mfma_f32_16x16x32_bf16 v[156:159], v[108:111], v[124:127], v[156:159]
	v_mfma_f32_16x16x32_bf16 v[60:63], v[116:119], v[124:127], v[60:63]
	v_mfma_f32_16x16x32_bf16 v[148:151], v[108:111], v[132:135], v[148:151]
	v_mfma_f32_16x16x32_bf16 v[52:55], v[116:119], v[132:135], v[52:55]
	v_mfma_f32_16x16x32_bf16 v[140:143], v[108:111], v[172:175], v[140:143]
	v_mfma_f32_16x16x32_bf16 v[44:47], v[116:119], v[172:175], v[44:47]
	v_mfma_f32_16x16x32_bf16 v[100:103], v[108:111], v[194:197], v[100:103]
	v_mfma_f32_16x16x32_bf16 v[36:39], v[116:119], v[194:197], v[36:39]
	s_setprio 0
	s_barrier
	s_add_i32 s63, 0, 0x14000
	s_add_i32 s49, s49, s53
	v_add_u32_e32 v176, s63, v238
	v_lshl_add_u64 v[218:219], s[44:45], 0, v[160:161]
	s_mov_b32 m0, s49
	ds_read_b128 v[198:201], v176
	ds_read_b128 v[202:205], v176 offset:1024
	ds_read_b128 v[206:209], v176 offset:2048
	ds_read_b128 v[210:213], v176 offset:3072
	global_load_lds_dwordx4 v[218:219], off
	v_lshl_add_u64 v[220:221], s[44:45], 0, v[162:163]
	s_add_i32 m0, s49, 0x2000
	s_nop 0
	global_load_lds_dwordx4 v[220:221], off
	s_barrier
	s_waitcnt lgkmcnt(0)
	s_setprio 1
	s_waitcnt lgkmcnt(0)
	v_mfma_f32_16x16x32_bf16 v[152:155], v[198:201], v[120:123], v[152:155]
	v_mfma_f32_16x16x32_bf16 v[56:59], v[206:209], v[120:123], v[56:59]
	v_mfma_f32_16x16x32_bf16 v[48:51], v[206:209], v[128:131], v[48:51]
	v_mfma_f32_16x16x32_bf16 v[40:43], v[206:209], v[168:171], v[40:43]
	v_mfma_f32_16x16x32_bf16 v[96:99], v[198:201], v[190:193], v[96:99]
	v_mfma_f32_16x16x32_bf16 v[32:35], v[206:209], v[190:193], v[32:35]
	v_mfma_f32_16x16x32_bf16 v[152:155], v[202:205], v[124:127], v[152:155]
	v_mfma_f32_16x16x32_bf16 v[56:59], v[210:213], v[124:127], v[56:59]
	v_mfma_f32_16x16x32_bf16 v[120:123], v[198:201], v[128:131], v[144:147]
	v_mfma_f32_16x16x32_bf16 v[48:51], v[210:213], v[132:135], v[48:51]
	v_mfma_f32_16x16x32_bf16 v[124:127], v[198:201], v[168:171], v[136:139]
	v_mfma_f32_16x16x32_bf16 v[40:43], v[210:213], v[172:175], v[40:43]
	v_mfma_f32_16x16x32_bf16 v[96:99], v[202:205], v[194:197], v[96:99]
	v_mfma_f32_16x16x32_bf16 v[32:35], v[210:213], v[194:197], v[32:35]
	v_mfma_f32_16x16x32_bf16 v[120:123], v[202:205], v[132:135], v[120:123]
	v_mfma_f32_16x16x32_bf16 v[124:127], v[202:205], v[172:175], v[124:127]
	s_setprio 0
	s_mov_b32 m0, s54
	v_lshl_add_u64 v[240:241], s[46:47], 0, v[160:161]
	s_barrier
	ds_read_b128 v[128:131], v239 offset:16384
	ds_read_b128 v[132:135], v239 offset:17408
	ds_read_b128 v[136:139], v239 offset:18432
	ds_read_b128 v[144:147], v239 offset:19456
	ds_read_b128 v[168:171], v239 offset:20480
	ds_read_b128 v[172:175], v239 offset:21504
	ds_read_b128 v[190:193], v239 offset:22528
	ds_read_b128 v[194:197], v239 offset:23552
	global_load_lds_dwordx4 v[240:241], off
	v_lshl_add_u64 v[242:243], s[46:47], 0, v[162:163]
	s_mov_b32 m0, s55
	s_nop 0
	global_load_lds_dwordx4 v[242:243], off
	s_barrier
	s_waitcnt lgkmcnt(0)
	s_setprio 1
	s_waitcnt lgkmcnt(0)
	v_mfma_f32_16x16x32_bf16 v[92:95], v[104:107], v[128:131], v[92:95]
	v_mfma_f32_16x16x32_bf16 v[28:31], v[112:115], v[128:131], v[28:31]
	v_mfma_f32_16x16x32_bf16 v[84:87], v[104:107], v[136:139], v[84:87]
	v_mfma_f32_16x16x32_bf16 v[20:23], v[112:115], v[136:139], v[20:23]
	v_mfma_f32_16x16x32_bf16 v[76:79], v[104:107], v[168:171], v[76:79]
	v_mfma_f32_16x16x32_bf16 v[12:15], v[112:115], v[168:171], v[12:15]
	v_mfma_f32_16x16x32_bf16 v[68:71], v[104:107], v[190:193], v[68:71]
	v_mfma_f32_16x16x32_bf16 v[4:7], v[112:115], v[190:193], v[4:7]
	v_mfma_f32_16x16x32_bf16 v[92:95], v[108:111], v[132:135], v[92:95]
	v_mfma_f32_16x16x32_bf16 v[28:31], v[116:119], v[132:135], v[28:31]
	v_mfma_f32_16x16x32_bf16 v[84:87], v[108:111], v[144:147], v[84:87]
	v_mfma_f32_16x16x32_bf16 v[20:23], v[116:119], v[144:147], v[20:23]
	v_mfma_f32_16x16x32_bf16 v[76:79], v[108:111], v[172:175], v[76:79]
	v_mfma_f32_16x16x32_bf16 v[12:15], v[116:119], v[172:175], v[12:15]
	v_mfma_f32_16x16x32_bf16 v[68:71], v[108:111], v[194:197], v[68:71]
	v_mfma_f32_16x16x32_bf16 v[4:7], v[116:119], v[194:197], v[4:7]
	s_setprio 0
	s_barrier
	s_add_u32 s64, s44, 0x40000
	s_addc_u32 s65, s45, 0
	s_add_i32 s49, s63, s53
	v_lshl_add_u64 v[104:105], s[64:65], 0, v[160:161]
	s_mov_b32 m0, s49
	s_nop 0
	global_load_lds_dwordx4 v[104:105], off
	v_lshl_add_u64 v[104:105], s[64:65], 0, v[162:163]
	s_add_i32 m0, s49, 0x2000
	s_nop 0
	global_load_lds_dwordx4 v[104:105], off
	s_waitcnt vmcnt(6)
	s_barrier
	s_setprio 1
	v_mfma_f32_16x16x32_bf16 v[88:91], v[198:201], v[128:131], v[88:91]
	v_mfma_f32_16x16x32_bf16 v[24:27], v[206:209], v[128:131], v[24:27]
	v_mfma_f32_16x16x32_bf16 v[80:83], v[198:201], v[136:139], v[80:83]
	v_mfma_f32_16x16x32_bf16 v[16:19], v[206:209], v[136:139], v[16:19]
	v_mfma_f32_16x16x32_bf16 v[72:75], v[198:201], v[168:171], v[72:75]
	v_mfma_f32_16x16x32_bf16 v[8:11], v[206:209], v[168:171], v[8:11]
	v_mfma_f32_16x16x32_bf16 v[64:67], v[198:201], v[190:193], v[64:67]
	v_mfma_f32_16x16x32_bf16 v[0:3], v[206:209], v[190:193], v[0:3]
	v_mfma_f32_16x16x32_bf16 v[88:91], v[202:205], v[132:135], v[88:91]
	v_mfma_f32_16x16x32_bf16 v[24:27], v[210:213], v[132:135], v[24:27]
	v_mfma_f32_16x16x32_bf16 v[80:83], v[202:205], v[144:147], v[80:83]
	v_mfma_f32_16x16x32_bf16 v[16:19], v[210:213], v[144:147], v[16:19]
	v_mfma_f32_16x16x32_bf16 v[72:75], v[202:205], v[172:175], v[72:75]
	v_mfma_f32_16x16x32_bf16 v[8:11], v[210:213], v[172:175], v[8:11]
	v_mfma_f32_16x16x32_bf16 v[64:67], v[202:205], v[194:197], v[64:67]
	v_mfma_f32_16x16x32_bf16 v[0:3], v[210:213], v[194:197], v[0:3]
	s_setprio 0
	s_add_i32 s49, 0, 0x18000
	v_add_u32_e32 v116, s49, v238
	s_barrier
	ds_read_b128 v[104:107], v116
	ds_read_b128 v[108:111], v116 offset:1024
	ds_read_b128 v[112:115], v116 offset:2048
	ds_read_b128 v[116:119], v116 offset:3072
	s_add_u32 s46, s46, 0x40000
	s_addc_u32 s47, s47, 0
	s_mov_b32 m0, s56
	v_lshl_add_u64 v[144:145], s[46:47], 0, v[160:161]
	ds_read_b128 v[128:131], v239 offset:32768
	ds_read_b128 v[132:135], v239 offset:33792
	ds_read_b128 v[136:139], v239 offset:34816
	ds_read_b128 v[168:171], v239 offset:35840
	ds_read_b128 v[172:175], v239 offset:36864
	ds_read_b128 v[190:193], v239 offset:37888
	ds_read_b128 v[194:197], v239 offset:38912
	ds_read_b128 v[198:201], v239 offset:39936
	global_load_lds_dwordx4 v[144:145], off
	v_lshl_add_u64 v[144:145], s[46:47], 0, v[162:163]
	s_mov_b32 m0, s57
	s_nop 0
	global_load_lds_dwordx4 v[144:145], off
	s_waitcnt lgkmcnt(8)
	s_barrier
	s_waitcnt lgkmcnt(0)
	s_setprio 1
	s_waitcnt lgkmcnt(0)
	v_mfma_f32_16x16x32_bf16 v[144:147], v[104:107], v[128:131], v[156:159]
	v_mfma_f32_16x16x32_bf16 v[156:159], v[108:111], v[132:135], v[144:147]
	v_mfma_f32_16x16x32_bf16 v[60:63], v[112:115], v[128:131], v[60:63]
	v_mfma_f32_16x16x32_bf16 v[144:147], v[104:107], v[136:139], v[148:151]
	v_mfma_f32_16x16x32_bf16 v[52:55], v[112:115], v[136:139], v[52:55]
	v_mfma_f32_16x16x32_bf16 v[140:143], v[104:107], v[172:175], v[140:143]
	v_mfma_f32_16x16x32_bf16 v[44:47], v[112:115], v[172:175], v[44:47]
	v_mfma_f32_16x16x32_bf16 v[100:103], v[104:107], v[194:197], v[100:103]
	v_mfma_f32_16x16x32_bf16 v[36:39], v[112:115], v[194:197], v[36:39]
	v_mfma_f32_16x16x32_bf16 v[60:63], v[116:119], v[132:135], v[60:63]
	v_mfma_f32_16x16x32_bf16 v[148:151], v[108:111], v[168:171], v[144:147]
	v_mfma_f32_16x16x32_bf16 v[52:55], v[116:119], v[168:171], v[52:55]
	v_mfma_f32_16x16x32_bf16 v[140:143], v[108:111], v[190:193], v[140:143]
	v_mfma_f32_16x16x32_bf16 v[44:47], v[116:119], v[190:193], v[44:47]
	v_mfma_f32_16x16x32_bf16 v[100:103], v[108:111], v[198:201], v[100:103]
	v_mfma_f32_16x16x32_bf16 v[36:39], v[116:119], v[198:201], v[36:39]
	s_setprio 0
	s_barrier
	s_add_i32 s46, 0, 0x1c000
	v_add_u32_e32 v144, s46, v238
	s_add_i32 s47, s49, s53
	ds_read_b128 v[202:205], v144
	ds_read_b128 v[206:209], v144 offset:1024
	ds_read_b128 v[210:213], v144 offset:2048
	ds_read_b128 v[214:217], v144 offset:3072
	v_lshl_add_u64 v[144:145], v[218:219], 0, s[24:25]
	s_mov_b32 m0, s47
	s_nop 0
	global_load_lds_dwordx4 v[144:145], off
	v_lshl_add_u64 v[144:145], v[220:221], 0, s[24:25]
	s_add_i32 m0, s47, 0x2000
	s_nop 0
	global_load_lds_dwordx4 v[144:145], off
	s_barrier
	s_waitcnt lgkmcnt(0)
	s_setprio 1
	s_waitcnt lgkmcnt(0)
	v_mfma_f32_16x16x32_bf16 v[144:147], v[202:205], v[128:131], v[152:155]
	v_mfma_f32_16x16x32_bf16 v[120:123], v[202:205], v[136:139], v[120:123]
	v_mfma_f32_16x16x32_bf16 v[152:155], v[206:209], v[132:135], v[144:147]
	v_mfma_f32_16x16x32_bf16 v[56:59], v[210:213], v[128:131], v[56:59]
	v_mfma_f32_16x16x32_bf16 v[144:147], v[206:209], v[168:171], v[120:123]
	v_mfma_f32_16x16x32_bf16 v[48:51], v[210:213], v[136:139], v[48:51]
	v_mfma_f32_16x16x32_bf16 v[120:123], v[202:205], v[172:175], v[124:127]
	v_mfma_f32_16x16x32_bf16 v[40:43], v[210:213], v[172:175], v[40:43]
	v_mfma_f32_16x16x32_bf16 v[96:99], v[202:205], v[194:197], v[96:99]
	v_mfma_f32_16x16x32_bf16 v[32:35], v[210:213], v[194:197], v[32:35]
	v_mfma_f32_16x16x32_bf16 v[56:59], v[214:217], v[132:135], v[56:59]
	v_mfma_f32_16x16x32_bf16 v[48:51], v[214:217], v[168:171], v[48:51]
	v_mfma_f32_16x16x32_bf16 v[136:139], v[206:209], v[190:193], v[120:123]
	v_mfma_f32_16x16x32_bf16 v[40:43], v[214:217], v[190:193], v[40:43]
	v_mfma_f32_16x16x32_bf16 v[96:99], v[206:209], v[198:201], v[96:99]
	v_mfma_f32_16x16x32_bf16 v[32:35], v[214:217], v[198:201], v[32:35]
	s_setprio 0
	s_mov_b32 m0, s59
	v_lshl_add_u64 v[198:199], v[240:241], 0, s[24:25]
	s_barrier
	ds_read_b128 v[120:123], v239 offset:49152
	ds_read_b128 v[124:127], v239 offset:50176
	ds_read_b128 v[128:131], v239 offset:51200
	ds_read_b128 v[132:135], v239 offset:52224
	ds_read_b128 v[168:171], v239 offset:53248
	ds_read_b128 v[172:175], v239 offset:54272
	ds_read_b128 v[190:193], v239 offset:55296
	ds_read_b128 v[194:197], v239 offset:56320
	global_load_lds_dwordx4 v[198:199], off
	v_lshl_add_u64 v[198:199], v[242:243], 0, s[24:25]
	s_mov_b32 m0, s60
	s_nop 0
	global_load_lds_dwordx4 v[198:199], off
	s_barrier
	s_waitcnt lgkmcnt(0)
	s_setprio 1
	s_waitcnt lgkmcnt(0)
	v_mfma_f32_16x16x32_bf16 v[92:95], v[104:107], v[120:123], v[92:95]
	v_mfma_f32_16x16x32_bf16 v[28:31], v[112:115], v[120:123], v[28:31]
	v_mfma_f32_16x16x32_bf16 v[84:87], v[104:107], v[128:131], v[84:87]
	v_mfma_f32_16x16x32_bf16 v[20:23], v[112:115], v[128:131], v[20:23]
	v_mfma_f32_16x16x32_bf16 v[76:79], v[104:107], v[168:171], v[76:79]
	v_mfma_f32_16x16x32_bf16 v[12:15], v[112:115], v[168:171], v[12:15]
	v_mfma_f32_16x16x32_bf16 v[68:71], v[104:107], v[190:193], v[68:71]
	v_mfma_f32_16x16x32_bf16 v[4:7], v[112:115], v[190:193], v[4:7]
	v_mfma_f32_16x16x32_bf16 v[92:95], v[108:111], v[124:127], v[92:95]
	v_mfma_f32_16x16x32_bf16 v[28:31], v[116:119], v[124:127], v[28:31]
	v_mfma_f32_16x16x32_bf16 v[84:87], v[108:111], v[132:135], v[84:87]
	v_mfma_f32_16x16x32_bf16 v[20:23], v[116:119], v[132:135], v[20:23]
	v_mfma_f32_16x16x32_bf16 v[76:79], v[108:111], v[172:175], v[76:79]
	v_mfma_f32_16x16x32_bf16 v[12:15], v[116:119], v[172:175], v[12:15]
	v_mfma_f32_16x16x32_bf16 v[68:71], v[108:111], v[194:197], v[68:71]
	v_mfma_f32_16x16x32_bf16 v[4:7], v[116:119], v[194:197], v[4:7]
	s_setprio 0
	s_barrier
	s_add_u32 s44, s44, 0x40080
	s_addc_u32 s45, s45, 0
	s_add_i32 s46, s46, s53
	v_lshl_add_u64 v[104:105], s[44:45], 0, v[160:161]
	s_mov_b32 m0, s46
	s_nop 0
	global_load_lds_dwordx4 v[104:105], off
	v_lshl_add_u64 v[104:105], s[44:45], 0, v[162:163]
	s_add_i32 m0, s46, 0x2000
	s_nop 0
	global_load_lds_dwordx4 v[104:105], off
	s_waitcnt vmcnt(6)
	s_barrier
	s_setprio 1
	v_mfma_f32_16x16x32_bf16 v[88:91], v[202:205], v[120:123], v[88:91]
	v_mfma_f32_16x16x32_bf16 v[24:27], v[210:213], v[120:123], v[24:27]
	v_mfma_f32_16x16x32_bf16 v[80:83], v[202:205], v[128:131], v[80:83]
	v_mfma_f32_16x16x32_bf16 v[16:19], v[210:213], v[128:131], v[16:19]
	v_mfma_f32_16x16x32_bf16 v[72:75], v[202:205], v[168:171], v[72:75]
	v_mfma_f32_16x16x32_bf16 v[8:11], v[210:213], v[168:171], v[8:11]
	v_mfma_f32_16x16x32_bf16 v[64:67], v[202:205], v[190:193], v[64:67]
	v_mfma_f32_16x16x32_bf16 v[0:3], v[210:213], v[190:193], v[0:3]
	v_mfma_f32_16x16x32_bf16 v[88:91], v[206:209], v[124:127], v[88:91]
	v_mfma_f32_16x16x32_bf16 v[24:27], v[214:217], v[124:127], v[24:27]
	v_mfma_f32_16x16x32_bf16 v[80:83], v[206:209], v[132:135], v[80:83]
	v_mfma_f32_16x16x32_bf16 v[16:19], v[214:217], v[132:135], v[16:19]
	v_mfma_f32_16x16x32_bf16 v[72:75], v[206:209], v[172:175], v[72:75]
	v_mfma_f32_16x16x32_bf16 v[8:11], v[214:217], v[172:175], v[8:11]
	v_mfma_f32_16x16x32_bf16 v[64:67], v[206:209], v[194:197], v[64:67]
	v_mfma_f32_16x16x32_bf16 v[0:3], v[214:217], v[194:197], v[0:3]
	s_setprio 0
	s_add_i32 s23, s23, 2
	s_add_u32 s42, s42, 0x100
	s_addc_u32 s43, s43, 0
	s_add_u32 s3, s3, 0x100
	s_addc_u32 s19, s19, 0
	s_cmp_gt_u32 s23, 13
	s_barrier
	s_cbranch_scc0 .LBB0_1609
	v_mov_b32_e32 v106, v223
	s_mov_b32 s3, s58
	v_mov_b32_e32 v200, v222
	s_mov_b32 s19, s52
	s_lshl_b32 s23, s2, 8
	s_lshl_b32 s42, s19, 6
	s_add_i32 s42, s42, s23
	s_lshl_b32 s23, s48, 7
	s_lshl_b32 s3, s3, 5
	s_add_i32 s3, s3, s23
	v_lshl_add_u32 v170, v106, 2, s3
	v_ashrrev_i32_e32 v171, 31, v170
	v_lshlrev_b64 v[106:107], 2, v[170:171]
	v_add_u32_e32 v104, s42, v200
	v_lshl_add_u64 v[192:193], s[4:5], 0, v[106:107]
	s_movk_i32 s3, 0x2000
	v_ashrrev_i32_e32 v105, 31, v104
	v_add_co_u32_e32 v120, vcc, s3, v192
	v_lshl_add_u64 v[104:105], v[104:105], 2, s[10:11]
	v_lshl_add_u64 v[190:191], s[14:15], 0, v[106:107]
	v_addc_co_u32_e32 v121, vcc, 0, v193, vcc
	global_load_dword v168, v[104:105], off
	v_add_co_u32_e32 v124, vcc, s3, v190
	v_lshl_add_u64 v[174:175], s[16:17], 0, v[106:107]
	s_nop 0
	v_addc_co_u32_e32 v125, vcc, 0, v191, vcc
	v_add_co_u32_e32 v128, vcc, s3, v174
	v_lshl_add_u64 v[172:173], s[6:7], 0, v[106:107]
	s_nop 0
	v_addc_co_u32_e32 v129, vcc, 0, v175, vcc
	v_add_co_u32_e32 v132, vcc, s3, v172
	global_load_dword v245, v[104:105], off offset:64
	global_load_dword v244, v[104:105], off offset:128
	global_load_dword v176, v[104:105], off offset:192
	global_load_dword v243, v[104:105], off offset:512
	global_load_dword v242, v[104:105], off offset:576
	global_load_dword v241, v[104:105], off offset:640
	global_load_dword v169, v[104:105], off offset:704
	v_addc_co_u32_e32 v133, vcc, 0, v173, vcc
	global_load_dwordx4 v[104:107], v[192:193], off
	global_load_dwordx4 v[108:111], v[190:191], off
	global_load_dwordx4 v[112:115], v[174:175], off
	global_load_dwordx4 v[116:119], v[172:173], off
	s_nop 0
	global_load_dwordx4 v[120:123], v[120:121], off offset:3072
	s_nop 0
	global_load_dwordx4 v[124:127], v[124:125], off offset:3072
	s_nop 0
	global_load_dwordx4 v[128:131], v[128:129], off offset:3072
	s_nop 0
	global_load_dwordx4 v[132:135], v[132:133], off offset:3072
	s_lshl_b32 s2, s2, 2
	v_readlane_b32 s42, v249, 58
	s_add_i32 s2, s19, s2
	v_readlane_b32 s43, v249, 59
	v_cmp_lt_i32_e64 s[44:45], 1, v200
	v_lshl_add_u32 v240, s2, 6, v200
	v_lshl_add_u64 v[196:197], v[170:171], 1, s[42:43]
	s_waitcnt vmcnt(0)
	v_fmamk_f32 v168, v168, 0x3a800000, v228
	v_rsq_f32_e32 v168, v168
	s_nop 0
	v_pk_mul_f32 v[208:209], v[156:157], v[168:169] op_sel_hi:[1,0]
	v_pk_mul_f32 v[204:205], v[152:153], v[168:169] op_sel_hi:[1,0]
	v_pk_mul_f32 v[206:207], v[158:159], v[168:169] op_sel_hi:[1,0]
	v_pk_mul_f32 v[210:211], v[154:155], v[168:169] op_sel_hi:[1,0]
	v_mov_b32_dpp v194, v208 row_ror:1 row_mask:0xf bank_mask:0xf
	v_mov_b32_dpp v202, v208 row_ror:2 row_mask:0xf bank_mask:0xf
	v_mov_b32_dpp v195, v209 row_ror:1 row_mask:0xf bank_mask:0xf
	v_mov_b32_dpp v203, v209 row_ror:2 row_mask:0xf bank_mask:0xf
	v_mov_b32_dpp v214, v204 row_ror:1 row_mask:0xf bank_mask:0xf
	v_mov_b32_dpp v216, v204 row_ror:2 row_mask:0xf bank_mask:0xf
	v_mov_b32_dpp v215, v205 row_ror:1 row_mask:0xf bank_mask:0xf
	v_mov_b32_dpp v217, v205 row_ror:2 row_mask:0xf bank_mask:0xf
	v_mov_b32_dpp v198, v206 row_ror:1 row_mask:0xf bank_mask:0xf
	v_mov_b32_dpp v212, v206 row_ror:2 row_mask:0xf bank_mask:0xf
	v_mov_b32_dpp v199, v207 row_ror:1 row_mask:0xf bank_mask:0xf
	v_mov_b32_dpp v213, v207 row_ror:2 row_mask:0xf bank_mask:0xf
	v_mov_b32_dpp v218, v210 row_ror:1 row_mask:0xf bank_mask:0xf
	v_mov_b32_dpp v220, v210 row_ror:2 row_mask:0xf bank_mask:0xf
	v_mov_b32_dpp v219, v211 row_ror:1 row_mask:0xf bank_mask:0xf
	v_mov_b32_dpp v221, v211 row_ror:2 row_mask:0xf bank_mask:0xf
	v_mov_b32_dpp v194, v208 row_shr:1 row_mask:0xf bank_mask:0xf
	v_mov_b32_dpp v202, v208 row_shr:2 row_mask:0xf bank_mask:0xf
	v_mov_b32_dpp v195, v209 row_shr:1 row_mask:0xf bank_mask:0xf
	v_mov_b32_dpp v203, v209 row_shr:2 row_mask:0xf bank_mask:0xf
	v_mov_b32_dpp v214, v204 row_shr:1 row_mask:0xf bank_mask:0xf
	v_mov_b32_dpp v216, v204 row_shr:2 row_mask:0xf bank_mask:0xf
	v_mov_b32_dpp v215, v205 row_shr:1 row_mask:0xf bank_mask:0xf
	v_mov_b32_dpp v217, v205 row_shr:2 row_mask:0xf bank_mask:0xf
	v_mov_b32_dpp v198, v206 row_shr:1 row_mask:0xf bank_mask:0xf
	v_mov_b32_dpp v212, v206 row_shr:2 row_mask:0xf bank_mask:0xf
	v_mov_b32_dpp v199, v207 row_shr:1 row_mask:0xf bank_mask:0xf
	v_mov_b32_dpp v213, v207 row_shr:2 row_mask:0xf bank_mask:0xf
	v_mov_b32_dpp v218, v210 row_shr:1 row_mask:0xf bank_mask:0xf
	v_mov_b32_dpp v220, v210 row_shr:2 row_mask:0xf bank_mask:0xf
	v_mov_b32_dpp v219, v211 row_shr:1 row_mask:0xf bank_mask:0xf
	v_mov_b32_dpp v221, v211 row_shr:2 row_mask:0xf bank_mask:0xf
	s_and_saveexec_b64 s[42:43], s[44:45]
	s_cbranch_execz .LBB0_1612
	v_pk_fma_f32 v[246:247], v[208:209], v[112:113], v[116:117]
	s_movk_i32 s3, 0x1600
	v_pk_fma_f32 v[194:195], v[108:109], v[194:195], v[246:247]
	v_pk_fma_f32 v[246:247], v[204:205], v[128:129], v[132:133]
	v_pk_fma_f32 v[194:195], v[104:105], v[202:203], v[194:195]
	v_pk_fma_f32 v[214:215], v[124:125], v[214:215], v[246:247]
	v_mul_f32_e32 v201, 0xbfb8aa3b, v194
	v_mul_f32_e32 v202, 0xbfb8aa3b, v195
	v_exp_f32_e32 v201, v201
	v_exp_f32_e32 v202, v202
	v_pk_fma_f32 v[214:215], v[120:121], v[216:217], v[214:215]
	v_add_f32_e32 v201, 1.0, v201
	v_add_f32_e32 v203, 1.0, v202
	v_rcp_f32_e32 v202, v201
	v_rcp_f32_e32 v203, v203
	s_nop 0
	v_pk_mul_f32 v[194:195], v[194:195], v[202:203]
	v_pk_fma_f32 v[202:203], v[206:207], v[114:115], v[118:119]
	v_pk_mul_f32 v[194:195], v[194:195], v[214:215]
	v_pk_fma_f32 v[198:199], v[110:111], v[198:199], v[202:203]
	v_cvt_pk_bf16_f32 v194, v194, v195
	v_pk_fma_f32 v[198:199], v[106:107], v[212:213], v[198:199]
	v_pk_fma_f32 v[212:213], v[210:211], v[130:131], v[134:135]
	v_mul_f32_e32 v201, 0xbfb8aa3b, v198
	v_exp_f32_e32 v201, v201
	v_mul_f32_e32 v202, 0xbfb8aa3b, v199
	v_exp_f32_e32 v203, v202
	v_pk_fma_f32 v[212:213], v[126:127], v[218:219], v[212:213]
	v_add_f32_e32 v201, 1.0, v201
	v_rcp_f32_e32 v202, v201
	v_add_f32_e32 v201, 1.0, v203
	v_rcp_f32_e32 v203, v201
	v_pk_fma_f32 v[212:213], v[122:123], v[220:221], v[212:213]
	v_pk_mul_f32 v[198:199], v[198:199], v[202:203]
	s_nop 0
	v_pk_mul_f32 v[198:199], v[198:199], v[212:213]
	s_nop 0
	v_cvt_pk_bf16_f32 v195, v198, v199
	v_mad_i64_i32 v[198:199], s[46:47], v240, s3, v[196:197]
	global_store_dwordx2 v[198:199], v[194:195], off

.LBB0_1614:
	s_or_b64 exec, exec, s[42:43]
	s_nop 0
	v_fmamk_f32 v152, v245, 0x3a800000, v228
	v_rsq_f32_e32 v158, v152
	v_fmamk_f32 v152, v244, 0x3a800000, v228
	v_rsq_f32_e32 v156, v152
	v_fmamk_f32 v152, v176, 0x3a800000, v228
	v_mov_b32_e32 v176, v200
	v_lshl_add_u64 v[212:213], s[48:49], 0, v[176:177]
	v_mad_u64_u32 v[154:155], s[48:49], v212, s3, 0
	v_mad_i32_i24 v155, v213, s3, v155
	v_mov_b32_dpp v212, v208 row_ror:1 row_mask:0xf bank_mask:0xf
	v_mov_b32_dpp v214, v208 row_ror:2 row_mask:0xf bank_mask:0xf
	v_mov_b32_dpp v213, v209 row_ror:1 row_mask:0xf bank_mask:0xf
	v_mov_b32_dpp v215, v209 row_ror:2 row_mask:0xf bank_mask:0xf
	v_mov_b32_dpp v208, v206 row_ror:1 row_mask:0xf bank_mask:0xf
	v_mov_b32_dpp v216, v206 row_ror:2 row_mask:0xf bank_mask:0xf
	v_mov_b32_dpp v209, v207 row_ror:1 row_mask:0xf bank_mask:0xf
	v_mov_b32_dpp v217, v207 row_ror:2 row_mask:0xf bank_mask:0xf
	v_mov_b32_dpp v206, v204 row_ror:1 row_mask:0xf bank_mask:0xf
	v_mov_b32_dpp v218, v204 row_ror:2 row_mask:0xf bank_mask:0xf
	v_mov_b32_dpp v207, v205 row_ror:1 row_mask:0xf bank_mask:0xf
	v_mov_b32_dpp v219, v205 row_ror:2 row_mask:0xf bank_mask:0xf
	v_pk_mul_f32 v[148:149], v[148:149], v[158:159] op_sel_hi:[1,0]
	v_mov_b32_dpp v204, v210 row_ror:1 row_mask:0xf bank_mask:0xf
	v_mov_b32_dpp v220, v210 row_ror:2 row_mask:0xf bank_mask:0xf
	v_mov_b32_dpp v205, v211 row_ror:1 row_mask:0xf bank_mask:0xf
	v_mov_b32_dpp v221, v211 row_ror:2 row_mask:0xf bank_mask:0xf
	v_mov_b32_dpp v212, v148 row_shr:1 row_mask:0xf bank_mask:0xf
	v_mov_b32_dpp v213, v149 row_shr:1 row_mask:0xf bank_mask:0xf
	v_pk_mul_f32 v[210:211], v[144:145], v[158:159] op_sel_hi:[1,0]
	v_pk_fma_f32 v[144:145], v[148:149], v[112:113], v[116:117]
	v_mov_b32_dpp v214, v148 row_shr:2 row_mask:0xf bank_mask:0xf
	v_mov_b32_dpp v215, v149 row_shr:2 row_mask:0xf bank_mask:0xf
	v_pk_fma_f32 v[144:145], v[108:109], v[212:213], v[144:145]
	v_mov_b32_dpp v206, v210 row_shr:1 row_mask:0xf bank_mask:0xf
	v_pk_fma_f32 v[144:145], v[104:105], v[214:215], v[144:145]
	v_mov_b32_dpp v207, v211 row_shr:1 row_mask:0xf bank_mask:0xf
	v_mul_f32_e32 v153, 0xbfb8aa3b, v144
	v_exp_f32_e32 v153, v153
	v_mul_f32_e32 v157, 0xbfb8aa3b, v145
	v_exp_f32_e32 v157, v157
	v_pk_fma_f32 v[214:215], v[210:211], v[128:129], v[132:133]
	v_add_f32_e32 v153, 1.0, v153
	v_rcp_f32_e32 v212, v153
	v_add_f32_e32 v153, 1.0, v157
	v_rcp_f32_e32 v213, v153
	v_mov_b32_dpp v218, v210 row_shr:2 row_mask:0xf bank_mask:0xf
	v_mov_b32_dpp v219, v211 row_shr:2 row_mask:0xf bank_mask:0xf
	v_pk_fma_f32 v[206:207], v[124:125], v[206:207], v[214:215]
	v_pk_mul_f32 v[144:145], v[144:145], v[212:213]
	v_pk_fma_f32 v[206:207], v[120:121], v[218:219], v[206:207]
	v_pk_mul_f32 v[150:151], v[150:151], v[158:159] op_sel_hi:[1,0]
	v_pk_mul_f32 v[144:145], v[144:145], v[206:207]
	v_pk_fma_f32 v[206:207], v[150:151], v[114:115], v[118:119]
	v_mov_b32_dpp v208, v150 row_shr:1 row_mask:0xf bank_mask:0xf
	v_mov_b32_dpp v209, v151 row_shr:1 row_mask:0xf bank_mask:0xf
	v_mov_b32_dpp v216, v150 row_shr:2 row_mask:0xf bank_mask:0xf
	v_mov_b32_dpp v217, v151 row_shr:2 row_mask:0xf bank_mask:0xf
	v_pk_fma_f32 v[206:207], v[110:111], v[208:209], v[206:207]
	v_pk_mul_f32 v[146:147], v[146:147], v[158:159] op_sel_hi:[1,0]
	v_pk_fma_f32 v[206:207], v[106:107], v[216:217], v[206:207]
	v_pk_fma_f32 v[212:213], v[146:147], v[130:131], v[134:135]
	v_mul_f32_e32 v153, 0xbfb8aa3b, v206
	v_exp_f32_e32 v153, v153
	v_mul_f32_e32 v157, 0xbfb8aa3b, v207
	v_exp_f32_e32 v157, v157
	v_mov_b32_dpp v204, v146 row_shr:1 row_mask:0xf bank_mask:0xf
	v_add_f32_e32 v153, 1.0, v153
	v_rcp_f32_e32 v208, v153
	v_add_f32_e32 v153, 1.0, v157
	v_rcp_f32_e32 v209, v153
	v_mov_b32_dpp v205, v147 row_shr:1 row_mask:0xf bank_mask:0xf
	v_mov_b32_dpp v220, v146 row_shr:2 row_mask:0xf bank_mask:0xf
	v_mov_b32_dpp v221, v147 row_shr:2 row_mask:0xf bank_mask:0xf
	v_pk_fma_f32 v[204:205], v[126:127], v[204:205], v[212:213]
	v_pk_mul_f32 v[206:207], v[206:207], v[208:209]
	v_pk_fma_f32 v[204:205], v[122:123], v[220:221], v[204:205]
	s_movk_i32 s3, 0x1600
	v_pk_mul_f32 v[204:205], v[206:207], v[204:205]
	v_cvt_pk_bf16_f32 v206, v144, v145
	v_add_u32_e32 v144, 16, v240
	v_cvt_pk_bf16_f32 v207, v204, v205
	v_mad_i64_i32 v[144:145], s[48:49], v144, s3, v[196:197]
	global_store_dwordx2 v[144:145], v[206:207], off
	v_mov_b32_dpp v204, v148 row_ror:1 row_mask:0xf bank_mask:0xf
	v_mov_b32_dpp v206, v148 row_ror:2 row_mask:0xf bank_mask:0xf
	v_mov_b32_dpp v205, v149 row_ror:1 row_mask:0xf bank_mask:0xf
	v_mov_b32_dpp v207, v149 row_ror:2 row_mask:0xf bank_mask:0xf
	v_mov_b32_dpp v148, v150 row_ror:1 row_mask:0xf bank_mask:0xf
	v_mov_b32_dpp v208, v150 row_ror:2 row_mask:0xf bank_mask:0xf
	v_mov_b32_dpp v149, v151 row_ror:1 row_mask:0xf bank_mask:0xf
	v_mov_b32_dpp v209, v151 row_ror:2 row_mask:0xf bank_mask:0xf
	v_mov_b32_dpp v150, v210 row_ror:1 row_mask:0xf bank_mask:0xf
	v_mov_b32_dpp v212, v210 row_ror:2 row_mask:0xf bank_mask:0xf
	v_mov_b32_dpp v151, v211 row_ror:1 row_mask:0xf bank_mask:0xf
	v_mov_b32_dpp v213, v211 row_ror:2 row_mask:0xf bank_mask:0xf
	v_pk_mul_f32 v[140:141], v[140:141], v[156:157] op_sel_hi:[1,0]
	v_mov_b32_dpp v210, v146 row_ror:1 row_mask:0xf bank_mask:0xf
	v_mov_b32_dpp v214, v146 row_ror:2 row_mask:0xf bank_mask:0xf
	v_mov_b32_dpp v211, v147 row_ror:1 row_mask:0xf bank_mask:0xf
	v_mov_b32_dpp v215, v147 row_ror:2 row_mask:0xf bank_mask:0xf
	v_mov_b32_dpp v204, v140 row_shr:1 row_mask:0xf bank_mask:0xf
	v_mov_b32_dpp v205, v141 row_shr:1 row_mask:0xf bank_mask:0xf
	v_pk_fma_f32 v[146:147], v[140:141], v[112:113], v[116:117]
	v_mov_b32_dpp v206, v140 row_shr:2 row_mask:0xf bank_mask:0xf
	v_mov_b32_dpp v207, v141 row_shr:2 row_mask:0xf bank_mask:0xf
	v_pk_fma_f32 v[146:147], v[108:109], v[204:205], v[146:147]
	v_pk_mul_f32 v[136:137], v[136:137], v[156:157] op_sel_hi:[1,0]
	v_pk_fma_f32 v[146:147], v[104:105], v[206:207], v[146:147]
	v_pk_fma_f32 v[206:207], v[136:137], v[128:129], v[132:133]
	v_mul_f32_e32 v153, 0xbfb8aa3b, v146
	v_exp_f32_e32 v153, v153
	v_mul_f32_e32 v157, 0xbfb8aa3b, v147
	v_exp_f32_e32 v157, v157
	v_mov_b32_dpp v150, v136 row_shr:1 row_mask:0xf bank_mask:0xf
	v_add_f32_e32 v153, 1.0, v153
	v_rcp_f32_e32 v204, v153
	v_add_f32_e32 v153, 1.0, v157
	v_rcp_f32_e32 v205, v153
	v_mov_b32_dpp v151, v137 row_shr:1 row_mask:0xf bank_mask:0xf
	v_mov_b32_dpp v212, v136 row_shr:2 row_mask:0xf bank_mask:0xf
	v_mov_b32_dpp v213, v137 row_shr:2 row_mask:0xf bank_mask:0xf
	v_pk_fma_f32 v[150:151], v[124:125], v[150:151], v[206:207]
	v_pk_mul_f32 v[146:147], v[146:147], v[204:205]
	v_pk_fma_f32 v[150:151], v[120:121], v[212:213], v[150:151]
	v_pk_mul_f32 v[142:143], v[142:143], v[156:157] op_sel_hi:[1,0]
	v_pk_mul_f32 v[146:147], v[146:147], v[150:151]
	v_pk_mul_f32 v[150:151], v[138:139], v[156:157] op_sel_hi:[1,0]
	v_mov_b32_dpp v148, v142 row_shr:1 row_mask:0xf bank_mask:0xf
	v_mov_b32_dpp v149, v143 row_shr:1 row_mask:0xf bank_mask:0xf
	v_pk_fma_f32 v[138:139], v[142:143], v[114:115], v[118:119]
	v_mov_b32_dpp v208, v142 row_shr:2 row_mask:0xf bank_mask:0xf
	v_mov_b32_dpp v209, v143 row_shr:2 row_mask:0xf bank_mask:0xf
	v_pk_fma_f32 v[138:139], v[110:111], v[148:149], v[138:139]
	v_mov_b32_dpp v210, v150 row_shr:1 row_mask:0xf bank_mask:0xf
	v_pk_fma_f32 v[138:139], v[106:107], v[208:209], v[138:139]
	v_mov_b32_dpp v211, v151 row_shr:1 row_mask:0xf bank_mask:0xf
	v_mul_f32_e32 v148, 0xbfb8aa3b, v138
	v_mul_f32_e32 v149, 0xbfb8aa3b, v139
	v_exp_f32_e32 v148, v148
	v_exp_f32_e32 v149, v149
	v_pk_fma_f32 v[204:205], v[150:151], v[130:131], v[134:135]
	v_mov_b32_dpp v214, v150 row_shr:2 row_mask:0xf bank_mask:0xf
	v_add_f32_e32 v148, 1.0, v148
	v_add_f32_e32 v149, 1.0, v149
	v_rcp_f32_e32 v148, v148
	v_rcp_f32_e32 v149, v149
	v_mov_b32_dpp v215, v151 row_shr:2 row_mask:0xf bank_mask:0xf
	v_pk_fma_f32 v[204:205], v[126:127], v[210:211], v[204:205]
	v_cvt_pk_bf16_f32 v146, v146, v147
	v_pk_fma_f32 v[204:205], v[122:123], v[214:215], v[204:205]
	v_pk_mul_f32 v[138:139], v[138:139], v[148:149]
	v_rsq_f32_e32 v152, v152
	v_pk_mul_f32 v[138:139], v[138:139], v[204:205]
	v_cvt_pk_bf16_f32 v147, v138, v139
	v_add_u32_e32 v138, 32, v240
	v_mad_i64_i32 v[138:139], s[48:49], v138, s3, v[196:197]
	global_store_dwordx2 v[138:139], v[146:147], off
	v_mov_b32_dpp v146, v140 row_ror:1 row_mask:0xf bank_mask:0xf
	v_mov_b32_dpp v148, v140 row_ror:2 row_mask:0xf bank_mask:0xf
	v_mov_b32_dpp v147, v141 row_ror:1 row_mask:0xf bank_mask:0xf
	v_mov_b32_dpp v149, v141 row_ror:2 row_mask:0xf bank_mask:0xf
	v_mov_b32_dpp v140, v142 row_ror:1 row_mask:0xf bank_mask:0xf
	v_mov_b32_dpp v204, v142 row_ror:2 row_mask:0xf bank_mask:0xf
	v_mov_b32_dpp v141, v143 row_ror:1 row_mask:0xf bank_mask:0xf
	v_mov_b32_dpp v205, v143 row_ror:2 row_mask:0xf bank_mask:0xf
	v_mov_b32_dpp v142, v136 row_ror:1 row_mask:0xf bank_mask:0xf
	v_mov_b32_dpp v206, v136 row_ror:2 row_mask:0xf bank_mask:0xf
	v_mov_b32_dpp v143, v137 row_ror:1 row_mask:0xf bank_mask:0xf
	v_mov_b32_dpp v207, v137 row_ror:2 row_mask:0xf bank_mask:0xf
	v_mov_b32_dpp v136, v150 row_ror:1 row_mask:0xf bank_mask:0xf
	v_mov_b32_dpp v208, v150 row_ror:2 row_mask:0xf bank_mask:0xf
	v_mov_b32_dpp v137, v151 row_ror:1 row_mask:0xf bank_mask:0xf
	v_mov_b32_dpp v209, v151 row_ror:2 row_mask:0xf bank_mask:0xf
	v_pk_mul_f32 v[150:151], v[100:101], v[152:153] op_sel_hi:[1,0]
	v_pk_mul_f32 v[210:211], v[96:97], v[152:153] op_sel_hi:[1,0]
	v_cmp_lt_i32_e64 s[42:43], 13, v200
	v_mov_b32_dpp v146, v150 row_shr:1 row_mask:0xf bank_mask:0xf
	v_mov_b32_dpp v148, v150 row_shr:2 row_mask:0xf bank_mask:0xf
	v_mov_b32_dpp v147, v151 row_shr:1 row_mask:0xf bank_mask:0xf
	v_mov_b32_dpp v149, v151 row_shr:2 row_mask:0xf bank_mask:0xf
	v_pk_fma_f32 v[150:151], v[150:151], v[112:113], v[116:117]
	v_mov_b32_dpp v142, v210 row_shr:1 row_mask:0xf bank_mask:0xf
	v_pk_fma_f32 v[146:147], v[108:109], v[146:147], v[150:151]
	v_mov_b32_dpp v143, v211 row_shr:1 row_mask:0xf bank_mask:0xf
	v_pk_fma_f32 v[146:147], v[104:105], v[148:149], v[146:147]
	v_pk_fma_f32 v[150:151], v[210:211], v[128:129], v[132:133]
	v_mul_f32_e32 v148, 0xbfb8aa3b, v146
	v_mul_f32_e32 v149, 0xbfb8aa3b, v147
	v_exp_f32_e32 v148, v148
	v_exp_f32_e32 v149, v149
	v_mov_b32_dpp v206, v210 row_shr:2 row_mask:0xf bank_mask:0xf
	v_mov_b32_dpp v207, v211 row_shr:2 row_mask:0xf bank_mask:0xf
	v_add_f32_e32 v148, 1.0, v148
	v_add_f32_e32 v149, 1.0, v149
	v_rcp_f32_e32 v148, v148
	v_rcp_f32_e32 v149, v149
	v_pk_fma_f32 v[142:143], v[124:125], v[142:143], v[150:151]
	v_lshl_add_u64 v[198:199], v[170:171], 2, s[12:13]
	v_pk_fma_f32 v[142:143], v[120:121], v[206:207], v[142:143]
	v_pk_mul_f32 v[146:147], v[146:147], v[148:149]
	v_pk_mul_f32 v[148:149], v[98:99], v[152:153] op_sel_hi:[1,0]
	v_pk_mul_f32 v[142:143], v[146:147], v[142:143]
	v_pk_mul_f32 v[146:147], v[102:103], v[152:153] op_sel_hi:[1,0]
	v_mov_b32_dpp v136, v148 row_shr:1 row_mask:0xf bank_mask:0xf
	v_mov_b32_dpp v208, v148 row_shr:2 row_mask:0xf bank_mask:0xf
	v_mov_b32_dpp v140, v146 row_shr:1 row_mask:0xf bank_mask:0xf
	v_mov_b32_dpp v204, v146 row_shr:2 row_mask:0xf bank_mask:0xf
	v_mov_b32_dpp v141, v147 row_shr:1 row_mask:0xf bank_mask:0xf
	v_mov_b32_dpp v205, v147 row_shr:2 row_mask:0xf bank_mask:0xf
	v_pk_fma_f32 v[146:147], v[146:147], v[114:115], v[118:119]
	v_mov_b32_dpp v137, v149 row_shr:1 row_mask:0xf bank_mask:0xf
	v_pk_fma_f32 v[140:141], v[110:111], v[140:141], v[146:147]
	v_mov_b32_dpp v209, v149 row_shr:2 row_mask:0xf bank_mask:0xf
	v_pk_fma_f32 v[140:141], v[106:107], v[204:205], v[140:141]
	v_pk_fma_f32 v[148:149], v[148:149], v[130:131], v[134:135]
	v_mul_f32_e32 v146, 0xbfb8aa3b, v140
	v_mul_f32_e32 v147, 0xbfb8aa3b, v141
	v_exp_f32_e32 v146, v146
	v_exp_f32_e32 v147, v147
	v_pk_fma_f32 v[136:137], v[126:127], v[136:137], v[148:149]
	s_movk_i32 s19, 0x1600
	v_add_f32_e32 v146, 1.0, v146
	v_add_f32_e32 v147, 1.0, v147
	v_rcp_f32_e32 v146, v146
	v_rcp_f32_e32 v147, v147
	v_pk_fma_f32 v[136:137], v[122:123], v[208:209], v[136:137]
	v_pk_mul_f32 v[140:141], v[140:141], v[146:147]
	s_nop 0
	v_pk_mul_f32 v[136:137], v[140:141], v[136:137]
	v_cvt_pk_bf16_f32 v140, v142, v143
	v_cvt_pk_bf16_f32 v141, v136, v137
	v_add_u32_e32 v136, 48, v240
	v_mad_i64_i32 v[142:143], s[48:49], v136, s3, v[196:197]
	global_store_dwordx2 v[142:143], v[140:141], off
	s_and_saveexec_b64 s[48:49], s[42:43]
	s_cbranch_execz .LBB0_1616
	v_lshl_add_u64 v[136:137], v[198:199], 0, v[154:155]
	v_pk_mul_f32 v[102:103], v[102:103], v[152:153] op_sel_hi:[1,0]
	v_pk_mul_f32 v[100:101], v[100:101], v[152:153] op_sel_hi:[1,0]
	global_store_dwordx4 v[136:137], v[100:103], off
	v_pk_mul_f32 v[98:99], v[98:99], v[152:153] op_sel_hi:[1,0]
	v_pk_mul_f32 v[96:97], v[96:97], v[152:153] op_sel_hi:[1,0]
	v_add_co_u32_e32 v100, vcc, 0x2000, v136
	s_nop 1
	v_addc_co_u32_e32 v101, vcc, 0, v137, vcc
	global_store_dwordx4 v[100:101], v[96:99], off offset:3072
.LBB0_1616:
	s_or_b64 exec, exec, s[48:49]
	s_nop 0
	v_fmamk_f32 v96, v243, 0x3a800000, v228
	v_rsq_f32_e32 v102, v96
	s_nop 0
	v_pk_mul_f32 v[146:147], v[92:93], v[102:103] op_sel_hi:[1,0]
	v_pk_mul_f32 v[148:149], v[88:89], v[102:103] op_sel_hi:[1,0]
	v_pk_mul_f32 v[150:151], v[94:95], v[102:103] op_sel_hi:[1,0]
	v_pk_mul_f32 v[204:205], v[90:91], v[102:103] op_sel_hi:[1,0]
	s_add_i32 s2, s2, 2
	v_mov_b32_dpp v96, v146 row_ror:1 row_mask:0xf bank_mask:0xf
	v_mov_b32_dpp v98, v146 row_ror:2 row_mask:0xf bank_mask:0xf
	v_mov_b32_dpp v97, v147 row_ror:1 row_mask:0xf bank_mask:0xf
	v_mov_b32_dpp v99, v147 row_ror:2 row_mask:0xf bank_mask:0xf
	v_mov_b32_dpp v100, v148 row_ror:1 row_mask:0xf bank_mask:0xf
	v_mov_b32_dpp v136, v148 row_ror:2 row_mask:0xf bank_mask:0xf
	v_mov_b32_dpp v101, v149 row_ror:1 row_mask:0xf bank_mask:0xf
	v_mov_b32_dpp v137, v149 row_ror:2 row_mask:0xf bank_mask:0xf
	v_mov_b32_dpp v140, v150 row_ror:1 row_mask:0xf bank_mask:0xf
	v_mov_b32_dpp v206, v150 row_ror:2 row_mask:0xf bank_mask:0xf
	v_mov_b32_dpp v141, v151 row_ror:1 row_mask:0xf bank_mask:0xf
	v_mov_b32_dpp v207, v151 row_ror:2 row_mask:0xf bank_mask:0xf
	v_mov_b32_dpp v208, v204 row_ror:1 row_mask:0xf bank_mask:0xf
	v_mov_b32_dpp v210, v204 row_ror:2 row_mask:0xf bank_mask:0xf
	v_mov_b32_dpp v209, v205 row_ror:1 row_mask:0xf bank_mask:0xf
	v_mov_b32_dpp v211, v205 row_ror:2 row_mask:0xf bank_mask:0xf
	v_lshl_add_u32 v171, s2, 6, v200
	v_mov_b32_dpp v96, v146 row_shr:1 row_mask:0xf bank_mask:0xf
	v_mov_b32_dpp v98, v146 row_shr:2 row_mask:0xf bank_mask:0xf
	v_mov_b32_dpp v97, v147 row_shr:1 row_mask:0xf bank_mask:0xf
	v_mov_b32_dpp v99, v147 row_shr:2 row_mask:0xf bank_mask:0xf
	v_mov_b32_dpp v100, v148 row_shr:1 row_mask:0xf bank_mask:0xf
	v_mov_b32_dpp v136, v148 row_shr:2 row_mask:0xf bank_mask:0xf
	v_mov_b32_dpp v101, v149 row_shr:1 row_mask:0xf bank_mask:0xf
	v_mov_b32_dpp v137, v149 row_shr:2 row_mask:0xf bank_mask:0xf
	v_mov_b32_dpp v140, v150 row_shr:1 row_mask:0xf bank_mask:0xf
	v_mov_b32_dpp v206, v150 row_shr:2 row_mask:0xf bank_mask:0xf
	v_mov_b32_dpp v141, v151 row_shr:1 row_mask:0xf bank_mask:0xf
	v_mov_b32_dpp v207, v151 row_shr:2 row_mask:0xf bank_mask:0xf
	v_mov_b32_dpp v208, v204 row_shr:1 row_mask:0xf bank_mask:0xf
	v_mov_b32_dpp v210, v204 row_shr:2 row_mask:0xf bank_mask:0xf
	v_mov_b32_dpp v209, v205 row_shr:1 row_mask:0xf bank_mask:0xf
	v_mov_b32_dpp v211, v205 row_shr:2 row_mask:0xf bank_mask:0xf
	s_and_saveexec_b64 s[48:49], s[44:45]
	s_cbranch_execz .LBB0_1618
	v_pk_fma_f32 v[212:213], v[146:147], v[112:113], v[116:117]
	s_nop 0
	v_pk_fma_f32 v[96:97], v[108:109], v[96:97], v[212:213]
	v_pk_fma_f32 v[212:213], v[148:149], v[128:129], v[132:133]
	v_pk_fma_f32 v[96:97], v[104:105], v[98:99], v[96:97]
	v_pk_fma_f32 v[100:101], v[124:125], v[100:101], v[212:213]
	v_mul_f32_e32 v98, 0xbfb8aa3b, v96
	v_mul_f32_e32 v99, 0xbfb8aa3b, v97
	v_exp_f32_e32 v98, v98
	v_exp_f32_e32 v99, v99
	v_pk_fma_f32 v[100:101], v[120:121], v[136:137], v[100:101]
	v_add_f32_e32 v98, 1.0, v98
	v_add_f32_e32 v99, 1.0, v99
	v_rcp_f32_e32 v98, v98
	v_rcp_f32_e32 v99, v99
	s_nop 0
	v_pk_mul_f32 v[96:97], v[96:97], v[98:99]
	v_pk_fma_f32 v[98:99], v[150:151], v[114:115], v[118:119]
	v_pk_mul_f32 v[96:97], v[96:97], v[100:101]
	v_pk_fma_f32 v[98:99], v[110:111], v[140:141], v[98:99]
	v_cvt_pk_bf16_f32 v96, v96, v97
	v_pk_fma_f32 v[98:99], v[106:107], v[206:207], v[98:99]
	s_nop 0
	v_mul_f32_e32 v103, 0xbfb8aa3b, v98
	v_mul_f32_e32 v136, 0xbfb8aa3b, v99
	v_exp_f32_e32 v103, v103
	v_exp_f32_e32 v136, v136
	v_add_f32_e32 v100, 1.0, v103
	v_add_f32_e32 v101, 1.0, v136
	v_rcp_f32_e32 v100, v100
	v_rcp_f32_e32 v101, v101
	v_pk_fma_f32 v[136:137], v[204:205], v[130:131], v[134:135]
	v_pk_mul_f32 v[98:99], v[98:99], v[100:101]
	v_pk_fma_f32 v[136:137], v[126:127], v[208:209], v[136:137]
	s_nop 0
	v_pk_fma_f32 v[136:137], v[122:123], v[210:211], v[136:137]
	s_nop 0
	v_pk_mul_f32 v[98:99], v[98:99], v[136:137]
	s_nop 0
	v_cvt_pk_bf16_f32 v97, v98, v99
	v_mad_i64_i32 v[98:99], s[64:65], v171, s19, v[196:197]
	global_store_dwordx2 v[98:99], v[96:97], off

.LBB0_1620:
	s_or_b64 exec, exec, s[48:49]
	s_nop 0
	v_lshl_add_u64 v[88:89], s[2:3], 0, v[176:177]
	v_mad_u64_u32 v[96:97], s[2:3], v88, s19, 0
	v_fmamk_f32 v88, v242, 0x3a800000, v228
	v_rsq_f32_e32 v136, v88
	v_fmamk_f32 v88, v241, 0x3a800000, v228
	v_rsq_f32_e32 v100, v88
	v_fmamk_f32 v88, v169, 0x3a800000, v228
	v_mad_i32_i24 v97, v89, s19, v97
	v_rsq_f32_e32 v98, v88
	v_mov_b32_dpp v88, v146 row_ror:1 row_mask:0xf bank_mask:0xf
	v_mov_b32_dpp v89, v147 row_ror:1 row_mask:0xf bank_mask:0xf
	v_pk_mul_f32 v[84:85], v[84:85], v[136:137] op_sel_hi:[1,0]
	v_mov_b32_dpp v90, v146 row_ror:2 row_mask:0xf bank_mask:0xf
	v_mov_b32_dpp v91, v147 row_ror:2 row_mask:0xf bank_mask:0xf
	v_mov_b32_dpp v88, v84 row_shr:1 row_mask:0xf bank_mask:0xf
	v_mov_b32_dpp v89, v85 row_shr:1 row_mask:0xf bank_mask:0xf
	v_pk_fma_f32 v[202:203], v[84:85], v[112:113], v[116:117]
	v_mov_b32_dpp v90, v84 row_shr:2 row_mask:0xf bank_mask:0xf
	v_mov_b32_dpp v91, v85 row_shr:2 row_mask:0xf bank_mask:0xf
	v_pk_fma_f32 v[88:89], v[108:109], v[88:89], v[202:203]
	v_pk_fma_f32 v[88:89], v[104:105], v[90:91], v[88:89]
	v_mul_f32_e32 v90, 0xbfb8aa3b, v88
	v_mul_f32_e32 v91, 0xbfb8aa3b, v89
	v_exp_f32_e32 v90, v90
	v_exp_f32_e32 v91, v91
	v_mov_b32_dpp v92, v150 row_ror:1 row_mask:0xf bank_mask:0xf
	v_add_f32_e32 v90, 1.0, v90
	v_add_f32_e32 v91, 1.0, v91
	v_rcp_f32_e32 v90, v90
	v_rcp_f32_e32 v91, v91
	v_mov_b32_dpp v93, v151 row_ror:1 row_mask:0xf bank_mask:0xf
	v_pk_mul_f32 v[86:87], v[86:87], v[136:137] op_sel_hi:[1,0]
	v_mov_b32_dpp v94, v150 row_ror:2 row_mask:0xf bank_mask:0xf
	v_mov_b32_dpp v95, v151 row_ror:2 row_mask:0xf bank_mask:0xf
	v_pk_mul_f32 v[88:89], v[88:89], v[90:91]
	v_mov_b32_dpp v92, v86 row_shr:1 row_mask:0xf bank_mask:0xf
	v_mov_b32_dpp v93, v87 row_shr:1 row_mask:0xf bank_mask:0xf
	v_pk_fma_f32 v[90:91], v[86:87], v[114:115], v[118:119]
	v_mov_b32_dpp v94, v86 row_shr:2 row_mask:0xf bank_mask:0xf
	v_mov_b32_dpp v95, v87 row_shr:2 row_mask:0xf bank_mask:0xf
	v_pk_fma_f32 v[90:91], v[110:111], v[92:93], v[90:91]
	v_pk_fma_f32 v[90:91], v[106:107], v[94:95], v[90:91]
	v_mul_f32_e32 v92, 0xbfb8aa3b, v90
	v_mul_f32_e32 v93, 0xbfb8aa3b, v91
	v_exp_f32_e32 v92, v92
	v_exp_f32_e32 v93, v93
	v_add_f32_e32 v92, 1.0, v92
	v_add_f32_e32 v93, 1.0, v93
	v_mov_b32_dpp v146, v148 row_ror:1 row_mask:0xf bank_mask:0xf
	v_mov_b32_dpp v150, v148 row_ror:2 row_mask:0xf bank_mask:0xf
	v_mov_b32_dpp v147, v149 row_ror:1 row_mask:0xf bank_mask:0xf
	v_mov_b32_dpp v151, v149 row_ror:2 row_mask:0xf bank_mask:0xf
	v_rcp_f32_e32 v92, v92
	v_rcp_f32_e32 v93, v93
	v_mov_b32_dpp v148, v204 row_ror:1 row_mask:0xf bank_mask:0xf
	v_mov_b32_dpp v149, v205 row_ror:1 row_mask:0xf bank_mask:0xf
	v_pk_mul_f32 v[80:81], v[80:81], v[136:137] op_sel_hi:[1,0]
	v_pk_mul_f32 v[82:83], v[82:83], v[136:137] op_sel_hi:[1,0]
	v_mov_b32_dpp v200, v204 row_ror:2 row_mask:0xf bank_mask:0xf
	v_mov_b32_dpp v201, v205 row_ror:2 row_mask:0xf bank_mask:0xf
	v_mov_b32_dpp v146, v80 row_shr:1 row_mask:0xf bank_mask:0xf
	v_mov_b32_dpp v147, v81 row_shr:1 row_mask:0xf bank_mask:0xf
	v_pk_fma_f32 v[202:203], v[80:81], v[128:129], v[132:133]
	v_mov_b32_dpp v148, v82 row_shr:1 row_mask:0xf bank_mask:0xf
	v_mov_b32_dpp v149, v83 row_shr:1 row_mask:0xf bank_mask:0xf
	v_pk_fma_f32 v[94:95], v[82:83], v[130:131], v[134:135]
	v_mov_b32_dpp v150, v80 row_shr:2 row_mask:0xf bank_mask:0xf
	v_mov_b32_dpp v151, v81 row_shr:2 row_mask:0xf bank_mask:0xf
	v_pk_fma_f32 v[146:147], v[124:125], v[146:147], v[202:203]
	v_mov_b32_dpp v200, v82 row_shr:2 row_mask:0xf bank_mask:0xf
	v_mov_b32_dpp v201, v83 row_shr:2 row_mask:0xf bank_mask:0xf
	v_pk_fma_f32 v[94:95], v[126:127], v[148:149], v[94:95]
	v_pk_fma_f32 v[146:147], v[120:121], v[150:151], v[146:147]
	v_pk_fma_f32 v[94:95], v[122:123], v[200:201], v[94:95]
	v_pk_mul_f32 v[90:91], v[90:91], v[92:93]
	v_pk_mul_f32 v[88:89], v[88:89], v[146:147]
	v_pk_mul_f32 v[90:91], v[90:91], v[94:95]
	v_cvt_pk_bf16_f32 v88, v88, v89
	v_cvt_pk_bf16_f32 v89, v90, v91
	v_add_u32_e32 v90, 16, v171
	s_movk_i32 s19, 0x1600
	v_mad_i64_i32 v[146:147], s[2:3], v90, s19, v[196:197]
	global_store_dwordx2 v[146:147], v[88:89], off
	v_mov_b32_dpp v88, v84 row_ror:1 row_mask:0xf bank_mask:0xf
	v_mov_b32_dpp v90, v84 row_ror:2 row_mask:0xf bank_mask:0xf
	v_mov_b32_dpp v89, v85 row_ror:1 row_mask:0xf bank_mask:0xf
	v_mov_b32_dpp v91, v85 row_ror:2 row_mask:0xf bank_mask:0xf
	v_mov_b32_dpp v84, v86 row_ror:1 row_mask:0xf bank_mask:0xf
	v_mov_b32_dpp v92, v86 row_ror:2 row_mask:0xf bank_mask:0xf
	v_mov_b32_dpp v85, v87 row_ror:1 row_mask:0xf bank_mask:0xf
	v_mov_b32_dpp v93, v87 row_ror:2 row_mask:0xf bank_mask:0xf
	v_mov_b32_dpp v86, v80 row_ror:1 row_mask:0xf bank_mask:0xf
	v_mov_b32_dpp v94, v80 row_ror:2 row_mask:0xf bank_mask:0xf
	v_mov_b32_dpp v87, v81 row_ror:1 row_mask:0xf bank_mask:0xf
	v_mov_b32_dpp v95, v81 row_ror:2 row_mask:0xf bank_mask:0xf
	v_pk_mul_f32 v[76:77], v[76:77], v[100:101] op_sel_hi:[1,0]
	v_mov_b32_dpp v80, v82 row_ror:1 row_mask:0xf bank_mask:0xf
	v_mov_b32_dpp v148, v82 row_ror:2 row_mask:0xf bank_mask:0xf
	v_mov_b32_dpp v81, v83 row_ror:1 row_mask:0xf bank_mask:0xf
	v_mov_b32_dpp v149, v83 row_ror:2 row_mask:0xf bank_mask:0xf
	v_mov_b32_dpp v88, v76 row_shr:1 row_mask:0xf bank_mask:0xf
	v_mov_b32_dpp v89, v77 row_shr:1 row_mask:0xf bank_mask:0xf
	v_pk_fma_f32 v[82:83], v[76:77], v[112:113], v[116:117]
	v_mov_b32_dpp v90, v76 row_shr:2 row_mask:0xf bank_mask:0xf
	v_mov_b32_dpp v91, v77 row_shr:2 row_mask:0xf bank_mask:0xf
	v_pk_fma_f32 v[82:83], v[108:109], v[88:89], v[82:83]
	v_pk_mul_f32 v[72:73], v[72:73], v[100:101] op_sel_hi:[1,0]
	v_pk_fma_f32 v[82:83], v[104:105], v[90:91], v[82:83]
	v_pk_fma_f32 v[90:91], v[72:73], v[128:129], v[132:133]
	v_mul_f32_e32 v88, 0xbfb8aa3b, v82
	v_mul_f32_e32 v89, 0xbfb8aa3b, v83
	v_exp_f32_e32 v88, v88
	v_exp_f32_e32 v89, v89
	v_mov_b32_dpp v86, v72 row_shr:1 row_mask:0xf bank_mask:0xf
	v_mov_b32_dpp v87, v73 row_shr:1 row_mask:0xf bank_mask:0xf
	v_add_f32_e32 v88, 1.0, v88
	v_add_f32_e32 v89, 1.0, v89
	v_rcp_f32_e32 v88, v88
	v_rcp_f32_e32 v89, v89
	v_mov_b32_dpp v94, v72 row_shr:2 row_mask:0xf bank_mask:0xf
	v_mov_b32_dpp v95, v73 row_shr:2 row_mask:0xf bank_mask:0xf
	v_pk_fma_f32 v[86:87], v[124:125], v[86:87], v[90:91]
	v_pk_mul_f32 v[82:83], v[82:83], v[88:89]
	v_pk_fma_f32 v[86:87], v[120:121], v[94:95], v[86:87]
	v_pk_mul_f32 v[78:79], v[78:79], v[100:101] op_sel_hi:[1,0]
	v_pk_mul_f32 v[82:83], v[82:83], v[86:87]
	v_pk_fma_f32 v[86:87], v[78:79], v[114:115], v[118:119]
	v_mov_b32_dpp v84, v78 row_shr:1 row_mask:0xf bank_mask:0xf
	v_mov_b32_dpp v85, v79 row_shr:1 row_mask:0xf bank_mask:0xf
	v_mov_b32_dpp v92, v78 row_shr:2 row_mask:0xf bank_mask:0xf
	v_mov_b32_dpp v93, v79 row_shr:2 row_mask:0xf bank_mask:0xf
	v_pk_fma_f32 v[84:85], v[110:111], v[84:85], v[86:87]
	v_pk_mul_f32 v[74:75], v[74:75], v[100:101] op_sel_hi:[1,0]
	v_pk_fma_f32 v[84:85], v[106:107], v[92:93], v[84:85]
	v_pk_fma_f32 v[88:89], v[74:75], v[130:131], v[134:135]
	v_mul_f32_e32 v86, 0xbfb8aa3b, v84
	v_mul_f32_e32 v87, 0xbfb8aa3b, v85
	v_exp_f32_e32 v86, v86
	v_exp_f32_e32 v87, v87
	v_mov_b32_dpp v80, v74 row_shr:1 row_mask:0xf bank_mask:0xf
	v_mov_b32_dpp v81, v75 row_shr:1 row_mask:0xf bank_mask:0xf
	v_add_f32_e32 v86, 1.0, v86
	v_add_f32_e32 v87, 1.0, v87
	v_rcp_f32_e32 v86, v86
	v_rcp_f32_e32 v87, v87
	v_mov_b32_dpp v148, v74 row_shr:2 row_mask:0xf bank_mask:0xf
	v_mov_b32_dpp v149, v75 row_shr:2 row_mask:0xf bank_mask:0xf
	v_pk_fma_f32 v[80:81], v[126:127], v[80:81], v[88:89]
	v_pk_mul_f32 v[84:85], v[84:85], v[86:87]
	v_pk_fma_f32 v[80:81], v[122:123], v[148:149], v[80:81]
	v_cvt_pk_bf16_f32 v82, v82, v83
	v_pk_mul_f32 v[80:81], v[84:85], v[80:81]
	v_cvt_pk_bf16_f32 v83, v80, v81
	v_add_u32_e32 v80, 32, v171
	v_mad_i64_i32 v[148:149], s[2:3], v80, s19, v[196:197]
	global_store_dwordx2 v[148:149], v[82:83], off
	v_mov_b32_dpp v80, v76 row_ror:1 row_mask:0xf bank_mask:0xf
	v_mov_b32_dpp v82, v76 row_ror:2 row_mask:0xf bank_mask:0xf
	v_mov_b32_dpp v81, v77 row_ror:1 row_mask:0xf bank_mask:0xf
	v_mov_b32_dpp v83, v77 row_ror:2 row_mask:0xf bank_mask:0xf
	v_mov_b32_dpp v76, v78 row_ror:1 row_mask:0xf bank_mask:0xf
	v_mov_b32_dpp v84, v78 row_ror:2 row_mask:0xf bank_mask:0xf
	v_mov_b32_dpp v77, v79 row_ror:1 row_mask:0xf bank_mask:0xf
	v_mov_b32_dpp v85, v79 row_ror:2 row_mask:0xf bank_mask:0xf
	v_mov_b32_dpp v78, v72 row_ror:1 row_mask:0xf bank_mask:0xf
	v_mov_b32_dpp v86, v72 row_ror:2 row_mask:0xf bank_mask:0xf
	v_mov_b32_dpp v79, v73 row_ror:1 row_mask:0xf bank_mask:0xf
	v_mov_b32_dpp v87, v73 row_ror:2 row_mask:0xf bank_mask:0xf
	v_mov_b32_dpp v72, v74 row_ror:1 row_mask:0xf bank_mask:0xf
	v_mov_b32_dpp v88, v74 row_ror:2 row_mask:0xf bank_mask:0xf
	v_mov_b32_dpp v73, v75 row_ror:1 row_mask:0xf bank_mask:0xf
	v_mov_b32_dpp v89, v75 row_ror:2 row_mask:0xf bank_mask:0xf
	v_pk_mul_f32 v[74:75], v[68:69], v[98:99] op_sel_hi:[1,0]
	v_pk_mul_f32 v[90:91], v[64:65], v[98:99] op_sel_hi:[1,0]
	s_nop 0
	v_mov_b32_dpp v80, v74 row_shr:1 row_mask:0xf bank_mask:0xf
	v_mov_b32_dpp v82, v74 row_shr:2 row_mask:0xf bank_mask:0xf
	v_mov_b32_dpp v81, v75 row_shr:1 row_mask:0xf bank_mask:0xf
	v_mov_b32_dpp v83, v75 row_shr:2 row_mask:0xf bank_mask:0xf
	v_pk_fma_f32 v[74:75], v[112:113], v[74:75], v[116:117]
	v_mov_b32_dpp v78, v90 row_shr:1 row_mask:0xf bank_mask:0xf
	v_pk_fma_f32 v[74:75], v[108:109], v[80:81], v[74:75]
	v_mov_b32_dpp v79, v91 row_shr:1 row_mask:0xf bank_mask:0xf
	v_pk_fma_f32 v[74:75], v[104:105], v[82:83], v[74:75]
	v_pk_fma_f32 v[82:83], v[90:91], v[128:129], v[132:133]
	v_mul_f32_e32 v80, 0xbfb8aa3b, v74
	v_mul_f32_e32 v81, 0xbfb8aa3b, v75
	v_exp_f32_e32 v80, v80
	v_exp_f32_e32 v81, v81
	v_mov_b32_dpp v86, v90 row_shr:2 row_mask:0xf bank_mask:0xf
	v_mov_b32_dpp v87, v91 row_shr:2 row_mask:0xf bank_mask:0xf
	v_add_f32_e32 v80, 1.0, v80
	v_add_f32_e32 v81, 1.0, v81
	v_rcp_f32_e32 v80, v80
	v_rcp_f32_e32 v81, v81
	v_pk_fma_f32 v[78:79], v[124:125], v[78:79], v[82:83]
	v_pk_mul_f32 v[74:75], v[74:75], v[80:81]
	v_pk_fma_f32 v[78:79], v[120:121], v[86:87], v[78:79]
	v_pk_mul_f32 v[80:81], v[66:67], v[98:99] op_sel_hi:[1,0]
	v_pk_mul_f32 v[74:75], v[74:75], v[78:79]
	v_pk_mul_f32 v[78:79], v[70:71], v[98:99] op_sel_hi:[1,0]
	v_mov_b32_dpp v72, v80 row_shr:1 row_mask:0xf bank_mask:0xf
	v_mov_b32_dpp v88, v80 row_shr:2 row_mask:0xf bank_mask:0xf
	v_mov_b32_dpp v76, v78 row_shr:1 row_mask:0xf bank_mask:0xf
	v_mov_b32_dpp v84, v78 row_shr:2 row_mask:0xf bank_mask:0xf
	v_mov_b32_dpp v77, v79 row_shr:1 row_mask:0xf bank_mask:0xf
	v_mov_b32_dpp v85, v79 row_shr:2 row_mask:0xf bank_mask:0xf
	v_pk_fma_f32 v[78:79], v[114:115], v[78:79], v[118:119]
	v_mov_b32_dpp v73, v81 row_shr:1 row_mask:0xf bank_mask:0xf
	v_pk_fma_f32 v[76:77], v[110:111], v[76:77], v[78:79]
	v_mov_b32_dpp v89, v81 row_shr:2 row_mask:0xf bank_mask:0xf
	v_pk_fma_f32 v[76:77], v[106:107], v[84:85], v[76:77]
	v_pk_fma_f32 v[80:81], v[80:81], v[130:131], v[134:135]
	v_mul_f32_e32 v78, 0xbfb8aa3b, v76
	v_mul_f32_e32 v79, 0xbfb8aa3b, v77
	v_exp_f32_e32 v78, v78
	v_exp_f32_e32 v79, v79
	v_pk_fma_f32 v[72:73], v[126:127], v[72:73], v[80:81]
	v_cvt_pk_bf16_f32 v74, v74, v75
	v_add_f32_e32 v78, 1.0, v78
	v_add_f32_e32 v79, 1.0, v79
	v_rcp_f32_e32 v78, v78
	v_rcp_f32_e32 v79, v79
	v_pk_fma_f32 v[72:73], v[122:123], v[88:89], v[72:73]
	v_pk_mul_f32 v[76:77], v[76:77], v[78:79]
	s_nop 0
	v_pk_mul_f32 v[72:73], v[76:77], v[72:73]
	s_nop 0
	v_cvt_pk_bf16_f32 v75, v72, v73
	v_add_u32_e32 v72, 48, v171
	v_mad_i64_i32 v[104:105], s[2:3], v72, s19, v[196:197]
	global_store_dwordx2 v[104:105], v[74:75], off
	s_and_saveexec_b64 s[2:3], s[42:43]
	s_cbranch_execz .LBB0_1622
	v_lshl_add_u64 v[72:73], v[198:199], 0, v[96:97]
	v_pk_mul_f32 v[70:71], v[70:71], v[98:99] op_sel_hi:[1,0]
	v_pk_mul_f32 v[68:69], v[68:69], v[98:99] op_sel_hi:[1,0]
	global_store_dwordx4 v[72:73], v[68:71], off
	v_pk_mul_f32 v[66:67], v[66:67], v[98:99] op_sel_hi:[1,0]
	v_pk_mul_f32 v[64:65], v[64:65], v[98:99] op_sel_hi:[1,0]
	v_add_co_u32_e32 v68, vcc, 0x2000, v72
	s_nop 1
	v_addc_co_u32_e32 v69, vcc, 0, v73, vcc
	global_store_dwordx4 v[68:69], v[64:67], off offset:3072
.LBB0_1622:
	s_or_b64 exec, exec, s[2:3]
	v_add_co_u32_e32 v80, vcc, 0x2000, v192
	global_load_dwordx4 v[64:67], v[192:193], off offset:64
	global_load_dwordx4 v[68:71], v[190:191], off offset:64
	global_load_dwordx4 v[72:75], v[174:175], off offset:64
	global_load_dwordx4 v[76:79], v[172:173], off offset:64
	v_addc_co_u32_e32 v81, vcc, 0, v193, vcc
	v_add_co_u32_e32 v84, vcc, 0x2000, v190
	v_mov_b32_e32 v169, v168
	s_nop 0
	v_addc_co_u32_e32 v85, vcc, 0, v191, vcc
	v_add_co_u32_e32 v88, vcc, 0x2000, v174
	global_load_dwordx4 v[80:83], v[80:81], off offset:3136
	s_nop 0
	global_load_dwordx4 v[84:87], v[84:85], off offset:3136
	v_addc_co_u32_e32 v89, vcc, 0, v175, vcc
	v_add_co_u32_e32 v92, vcc, 0x2000, v172
	global_load_dwordx4 v[88:91], v[88:89], off offset:3136
	s_nop 0
	v_addc_co_u32_e32 v93, vcc, 0, v173, vcc
	global_load_dwordx4 v[92:95], v[92:93], off offset:3136
	v_pk_mul_f32 v[108:109], v[60:61], v[168:169]
	v_pk_mul_f32 v[110:111], v[56:57], v[168:169]
	v_pk_mul_f32 v[112:113], v[62:63], v[168:169]
	v_pk_mul_f32 v[114:115], v[58:59], v[168:169]
	v_add_u32_e32 v106, 16, v170
	v_mov_b32_dpp v116, v108 row_ror:1 row_mask:0xf bank_mask:0xf
	v_mov_b32_dpp v120, v108 row_ror:2 row_mask:0xf bank_mask:0xf
	v_mov_b32_dpp v117, v109 row_ror:1 row_mask:0xf bank_mask:0xf
	v_mov_b32_dpp v121, v109 row_ror:2 row_mask:0xf bank_mask:0xf
	v_mov_b32_dpp v124, v110 row_ror:1 row_mask:0xf bank_mask:0xf
	v_mov_b32_dpp v128, v110 row_ror:2 row_mask:0xf bank_mask:0xf
	v_mov_b32_dpp v125, v111 row_ror:1 row_mask:0xf bank_mask:0xf
	v_mov_b32_dpp v129, v111 row_ror:2 row_mask:0xf bank_mask:0xf
	v_mov_b32_dpp v118, v112 row_ror:1 row_mask:0xf bank_mask:0xf
	v_mov_b32_dpp v122, v112 row_ror:2 row_mask:0xf bank_mask:0xf
	v_mov_b32_dpp v119, v113 row_ror:1 row_mask:0xf bank_mask:0xf
	v_mov_b32_dpp v123, v113 row_ror:2 row_mask:0xf bank_mask:0xf
	v_mov_b32_dpp v126, v114 row_ror:1 row_mask:0xf bank_mask:0xf
	v_mov_b32_dpp v130, v114 row_ror:2 row_mask:0xf bank_mask:0xf
	v_mov_b32_dpp v127, v115 row_ror:1 row_mask:0xf bank_mask:0xf
	v_mov_b32_dpp v131, v115 row_ror:2 row_mask:0xf bank_mask:0xf
	v_ashrrev_i32_e32 v107, 31, v106
	v_mov_b32_dpp v116, v108 row_shr:1 row_mask:0xf bank_mask:0xf
	v_mov_b32_dpp v120, v108 row_shr:2 row_mask:0xf bank_mask:0xf
	v_mov_b32_dpp v117, v109 row_shr:1 row_mask:0xf bank_mask:0xf
	v_mov_b32_dpp v121, v109 row_shr:2 row_mask:0xf bank_mask:0xf
	v_mov_b32_dpp v124, v110 row_shr:1 row_mask:0xf bank_mask:0xf
	v_mov_b32_dpp v128, v110 row_shr:2 row_mask:0xf bank_mask:0xf
	v_mov_b32_dpp v125, v111 row_shr:1 row_mask:0xf bank_mask:0xf
	v_mov_b32_dpp v129, v111 row_shr:2 row_mask:0xf bank_mask:0xf
	v_mov_b32_dpp v118, v112 row_shr:1 row_mask:0xf bank_mask:0xf
	v_mov_b32_dpp v122, v112 row_shr:2 row_mask:0xf bank_mask:0xf
	v_mov_b32_dpp v119, v113 row_shr:1 row_mask:0xf bank_mask:0xf
	v_mov_b32_dpp v123, v113 row_shr:2 row_mask:0xf bank_mask:0xf
	v_mov_b32_dpp v126, v114 row_shr:1 row_mask:0xf bank_mask:0xf
	v_mov_b32_dpp v130, v114 row_shr:2 row_mask:0xf bank_mask:0xf
	v_mov_b32_dpp v127, v115 row_shr:1 row_mask:0xf bank_mask:0xf
	v_mov_b32_dpp v131, v115 row_shr:2 row_mask:0xf bank_mask:0xf
	s_and_saveexec_b64 s[2:3], s[44:45]
	s_cbranch_execz .LBB0_1624
	s_waitcnt vmcnt(0)
	v_pk_fma_f32 v[132:133], v[108:109], v[72:73], v[76:77]
	v_readlane_b32 s48, v249, 58
	v_pk_fma_f32 v[116:117], v[68:69], v[116:117], v[132:133]
	v_pk_fma_f32 v[132:133], v[110:111], v[88:89], v[92:93]
	v_pk_fma_f32 v[116:117], v[64:65], v[120:121], v[116:117]
	v_pk_fma_f32 v[124:125], v[84:85], v[124:125], v[132:133]
	v_mul_f32_e32 v99, 0xbfb8aa3b, v116
	v_mul_f32_e32 v101, 0xbfb8aa3b, v117
	v_exp_f32_e32 v99, v99
	v_exp_f32_e32 v101, v101
	v_pk_fma_f32 v[124:125], v[80:81], v[128:129], v[124:125]
	v_readlane_b32 s49, v249, 59
	v_add_f32_e32 v99, 1.0, v99
	v_add_f32_e32 v101, 1.0, v101
	v_rcp_f32_e32 v120, v99
	v_rcp_f32_e32 v121, v101
	s_nop 0
	v_pk_mul_f32 v[116:117], v[116:117], v[120:121]
	v_pk_fma_f32 v[120:121], v[112:113], v[74:75], v[78:79]
	v_pk_mul_f32 v[116:117], v[116:117], v[124:125]
	v_pk_fma_f32 v[118:119], v[70:71], v[118:119], v[120:121]
	v_cvt_pk_bf16_f32 v116, v116, v117
	v_pk_fma_f32 v[118:119], v[66:67], v[122:123], v[118:119]
	v_pk_fma_f32 v[122:123], v[114:115], v[90:91], v[94:95]
	v_mul_f32_e32 v99, 0xbfb8aa3b, v118
	v_exp_f32_e32 v99, v99
	v_mul_f32_e32 v101, 0xbfb8aa3b, v119
	v_exp_f32_e32 v101, v101
	v_pk_fma_f32 v[122:123], v[86:87], v[126:127], v[122:123]
	v_add_f32_e32 v99, 1.0, v99
	v_rcp_f32_e32 v120, v99
	v_add_f32_e32 v99, 1.0, v101
	v_rcp_f32_e32 v121, v99
	v_pk_fma_f32 v[122:123], v[82:83], v[130:131], v[122:123]
	v_pk_mul_f32 v[118:119], v[118:119], v[120:121]
	s_nop 0
	v_pk_mul_f32 v[118:119], v[118:119], v[122:123]
	s_nop 0
	v_cvt_pk_bf16_f32 v117, v118, v119
	v_mov_b64_e32 v[118:119], s[48:49]
	v_mad_i64_i32 v[118:119], s[48:49], v240, s19, v[118:119]
	v_lshl_add_u64 v[118:119], v[106:107], 1, v[118:119]
	global_store_dwordx2 v[118:119], v[116:117], off

.LBB0_1626:
	s_or_b64 exec, exec, s[2:3]
	s_nop 0
	v_mov_b32_e32 v159, v158
	v_mov_b32_dpp v56, v108 row_ror:1 row_mask:0xf bank_mask:0xf
	v_mov_b32_dpp v58, v108 row_ror:2 row_mask:0xf bank_mask:0xf
	v_mov_b32_dpp v57, v109 row_ror:1 row_mask:0xf bank_mask:0xf
	v_mov_b32_dpp v59, v109 row_ror:2 row_mask:0xf bank_mask:0xf
	v_mov_b32_dpp v60, v112 row_ror:1 row_mask:0xf bank_mask:0xf
	v_mov_b32_dpp v62, v112 row_ror:2 row_mask:0xf bank_mask:0xf
	v_mov_b32_dpp v61, v113 row_ror:1 row_mask:0xf bank_mask:0xf
	v_mov_b32_dpp v63, v113 row_ror:2 row_mask:0xf bank_mask:0xf
	v_mov_b32_dpp v108, v110 row_ror:1 row_mask:0xf bank_mask:0xf
	v_mov_b32_dpp v112, v110 row_ror:2 row_mask:0xf bank_mask:0xf
	v_mov_b32_dpp v109, v111 row_ror:1 row_mask:0xf bank_mask:0xf
	v_mov_b32_dpp v113, v111 row_ror:2 row_mask:0xf bank_mask:0xf
	v_pk_mul_f32 v[52:53], v[52:53], v[158:159]
	v_mov_b32_dpp v110, v114 row_ror:1 row_mask:0xf bank_mask:0xf
	v_mov_b32_dpp v116, v114 row_ror:2 row_mask:0xf bank_mask:0xf
	v_mov_b32_dpp v111, v115 row_ror:1 row_mask:0xf bank_mask:0xf
	v_mov_b32_dpp v117, v115 row_ror:2 row_mask:0xf bank_mask:0xf
	v_mov_b32_dpp v56, v52 row_shr:1 row_mask:0xf bank_mask:0xf
	v_mov_b32_dpp v57, v53 row_shr:1 row_mask:0xf bank_mask:0xf
	s_waitcnt vmcnt(0)
	v_pk_fma_f32 v[114:115], v[52:53], v[72:73], v[76:77]
	v_mov_b32_dpp v58, v52 row_shr:2 row_mask:0xf bank_mask:0xf
	v_mov_b32_dpp v59, v53 row_shr:2 row_mask:0xf bank_mask:0xf
	v_pk_fma_f32 v[56:57], v[68:69], v[56:57], v[114:115]
	v_pk_mul_f32 v[54:55], v[54:55], v[158:159]
	v_pk_fma_f32 v[56:57], v[64:65], v[58:59], v[56:57]
	v_pk_mul_f32 v[48:49], v[48:49], v[158:159]
	v_mul_f32_e32 v58, 0xbfb8aa3b, v56
	v_mul_f32_e32 v59, 0xbfb8aa3b, v57
	v_exp_f32_e32 v58, v58
	v_exp_f32_e32 v59, v59
	v_mov_b32_dpp v60, v54 row_shr:1 row_mask:0xf bank_mask:0xf
	v_mov_b32_dpp v61, v55 row_shr:1 row_mask:0xf bank_mask:0xf
	v_add_f32_e32 v58, 1.0, v58
	v_add_f32_e32 v59, 1.0, v59
	v_rcp_f32_e32 v58, v58
	v_rcp_f32_e32 v59, v59
	v_mov_b32_dpp v62, v54 row_shr:2 row_mask:0xf bank_mask:0xf
	v_mov_b32_dpp v63, v55 row_shr:2 row_mask:0xf bank_mask:0xf
	v_pk_mul_f32 v[50:51], v[50:51], v[158:159]
	v_pk_mul_f32 v[56:57], v[56:57], v[58:59]
	v_pk_fma_f32 v[58:59], v[54:55], v[74:75], v[78:79]
	v_mov_b32_dpp v108, v48 row_shr:1 row_mask:0xf bank_mask:0xf
	v_pk_fma_f32 v[58:59], v[70:71], v[60:61], v[58:59]
	v_mov_b32_dpp v109, v49 row_shr:1 row_mask:0xf bank_mask:0xf
	v_pk_fma_f32 v[58:59], v[66:67], v[62:63], v[58:59]
	v_pk_fma_f32 v[114:115], v[48:49], v[88:89], v[92:93]
	v_mul_f32_e32 v60, 0xbfb8aa3b, v58
	v_mul_f32_e32 v61, 0xbfb8aa3b, v59
	v_exp_f32_e32 v60, v60
	v_exp_f32_e32 v61, v61
	v_mov_b32_dpp v110, v50 row_shr:1 row_mask:0xf bank_mask:0xf
	v_mov_b32_dpp v111, v51 row_shr:1 row_mask:0xf bank_mask:0xf
	v_add_f32_e32 v60, 1.0, v60
	v_add_f32_e32 v61, 1.0, v61
	v_rcp_f32_e32 v60, v60
	v_rcp_f32_e32 v61, v61
	v_pk_fma_f32 v[62:63], v[50:51], v[90:91], v[94:95]
	v_mov_b32_dpp v112, v48 row_shr:2 row_mask:0xf bank_mask:0xf
	v_mov_b32_dpp v113, v49 row_shr:2 row_mask:0xf bank_mask:0xf
	v_pk_fma_f32 v[108:109], v[84:85], v[108:109], v[114:115]
	v_mov_b32_dpp v116, v50 row_shr:2 row_mask:0xf bank_mask:0xf
	v_mov_b32_dpp v117, v51 row_shr:2 row_mask:0xf bank_mask:0xf
	v_pk_fma_f32 v[62:63], v[86:87], v[110:111], v[62:63]
	v_pk_fma_f32 v[108:109], v[80:81], v[112:113], v[108:109]
	v_pk_fma_f32 v[62:63], v[82:83], v[116:117], v[62:63]
	v_pk_mul_f32 v[58:59], v[58:59], v[60:61]
	v_pk_mul_f32 v[56:57], v[56:57], v[108:109]
	v_pk_mul_f32 v[58:59], v[58:59], v[62:63]
	v_cvt_pk_bf16_f32 v56, v56, v57
	v_cvt_pk_bf16_f32 v57, v58, v59
	global_store_dwordx2 v[144:145], v[56:57], off offset:32
	v_mov_b32_dpp v56, v52 row_ror:1 row_mask:0xf bank_mask:0xf
	v_mov_b32_dpp v58, v52 row_ror:2 row_mask:0xf bank_mask:0xf
	v_mov_b32_dpp v57, v53 row_ror:1 row_mask:0xf bank_mask:0xf
	v_mov_b32_dpp v59, v53 row_ror:2 row_mask:0xf bank_mask:0xf
	v_mov_b32_e32 v157, v156
	v_mov_b32_dpp v52, v54 row_ror:1 row_mask:0xf bank_mask:0xf
	v_mov_b32_dpp v60, v54 row_ror:2 row_mask:0xf bank_mask:0xf
	v_mov_b32_dpp v53, v55 row_ror:1 row_mask:0xf bank_mask:0xf
	v_mov_b32_dpp v61, v55 row_ror:2 row_mask:0xf bank_mask:0xf
	v_mov_b32_dpp v54, v48 row_ror:1 row_mask:0xf bank_mask:0xf
	v_mov_b32_dpp v62, v48 row_ror:2 row_mask:0xf bank_mask:0xf
	v_mov_b32_dpp v55, v49 row_ror:1 row_mask:0xf bank_mask:0xf
	v_mov_b32_dpp v63, v49 row_ror:2 row_mask:0xf bank_mask:0xf
	v_pk_mul_f32 v[44:45], v[44:45], v[156:157]
	v_mov_b32_dpp v48, v50 row_ror:1 row_mask:0xf bank_mask:0xf
	v_mov_b32_dpp v108, v50 row_ror:2 row_mask:0xf bank_mask:0xf
	v_mov_b32_dpp v49, v51 row_ror:1 row_mask:0xf bank_mask:0xf
	v_mov_b32_dpp v109, v51 row_ror:2 row_mask:0xf bank_mask:0xf
	v_mov_b32_dpp v56, v44 row_shr:1 row_mask:0xf bank_mask:0xf
	v_mov_b32_dpp v57, v45 row_shr:1 row_mask:0xf bank_mask:0xf
	v_pk_fma_f32 v[50:51], v[44:45], v[72:73], v[76:77]
	v_mov_b32_dpp v58, v44 row_shr:2 row_mask:0xf bank_mask:0xf
	v_mov_b32_dpp v59, v45 row_shr:2 row_mask:0xf bank_mask:0xf
	v_pk_fma_f32 v[50:51], v[68:69], v[56:57], v[50:51]
	v_pk_mul_f32 v[40:41], v[40:41], v[156:157]
	v_pk_fma_f32 v[50:51], v[64:65], v[58:59], v[50:51]
	v_pk_fma_f32 v[58:59], v[40:41], v[88:89], v[92:93]
	v_mul_f32_e32 v56, 0xbfb8aa3b, v50
	v_mul_f32_e32 v57, 0xbfb8aa3b, v51
	v_exp_f32_e32 v56, v56
	v_exp_f32_e32 v57, v57
	v_mov_b32_dpp v54, v40 row_shr:1 row_mask:0xf bank_mask:0xf
	v_mov_b32_dpp v55, v41 row_shr:1 row_mask:0xf bank_mask:0xf
	v_add_f32_e32 v56, 1.0, v56
	v_add_f32_e32 v57, 1.0, v57
	v_rcp_f32_e32 v56, v56
	v_rcp_f32_e32 v57, v57
	v_mov_b32_dpp v62, v40 row_shr:2 row_mask:0xf bank_mask:0xf
	v_mov_b32_dpp v63, v41 row_shr:2 row_mask:0xf bank_mask:0xf
	v_pk_fma_f32 v[54:55], v[84:85], v[54:55], v[58:59]
	v_pk_mul_f32 v[50:51], v[50:51], v[56:57]
	v_pk_fma_f32 v[54:55], v[80:81], v[62:63], v[54:55]
	v_pk_mul_f32 v[46:47], v[46:47], v[156:157]
	v_pk_mul_f32 v[50:51], v[50:51], v[54:55]
	v_pk_fma_f32 v[54:55], v[46:47], v[74:75], v[78:79]
	v_mov_b32_dpp v52, v46 row_shr:1 row_mask:0xf bank_mask:0xf
	v_mov_b32_dpp v53, v47 row_shr:1 row_mask:0xf bank_mask:0xf
	v_mov_b32_dpp v60, v46 row_shr:2 row_mask:0xf bank_mask:0xf
	v_mov_b32_dpp v61, v47 row_shr:2 row_mask:0xf bank_mask:0xf
	v_pk_fma_f32 v[52:53], v[70:71], v[52:53], v[54:55]
	v_pk_mul_f32 v[42:43], v[42:43], v[156:157]
	v_pk_fma_f32 v[52:53], v[66:67], v[60:61], v[52:53]
	v_pk_fma_f32 v[56:57], v[42:43], v[90:91], v[94:95]
	v_mul_f32_e32 v54, 0xbfb8aa3b, v52
	v_mul_f32_e32 v55, 0xbfb8aa3b, v53
	v_exp_f32_e32 v54, v54
	v_exp_f32_e32 v55, v55
	v_mov_b32_dpp v48, v42 row_shr:1 row_mask:0xf bank_mask:0xf
	v_mov_b32_dpp v49, v43 row_shr:1 row_mask:0xf bank_mask:0xf
	v_add_f32_e32 v54, 1.0, v54
	v_add_f32_e32 v55, 1.0, v55
	v_rcp_f32_e32 v54, v54
	v_rcp_f32_e32 v55, v55
	v_mov_b32_dpp v108, v42 row_shr:2 row_mask:0xf bank_mask:0xf
	v_mov_b32_dpp v109, v43 row_shr:2 row_mask:0xf bank_mask:0xf
	v_pk_fma_f32 v[48:49], v[86:87], v[48:49], v[56:57]
	v_pk_mul_f32 v[52:53], v[52:53], v[54:55]
	v_pk_fma_f32 v[48:49], v[82:83], v[108:109], v[48:49]
	v_cvt_pk_bf16_f32 v50, v50, v51
	v_pk_mul_f32 v[48:49], v[52:53], v[48:49]
	v_cvt_pk_bf16_f32 v51, v48, v49
	global_store_dwordx2 v[138:139], v[50:51], off offset:32
	v_mov_b32_dpp v48, v44 row_ror:1 row_mask:0xf bank_mask:0xf
	v_mov_b32_dpp v50, v44 row_ror:2 row_mask:0xf bank_mask:0xf
	v_mov_b32_dpp v49, v45 row_ror:1 row_mask:0xf bank_mask:0xf
	v_mov_b32_dpp v51, v45 row_ror:2 row_mask:0xf bank_mask:0xf
	v_mov_b32_dpp v44, v46 row_ror:1 row_mask:0xf bank_mask:0xf
	v_mov_b32_dpp v52, v46 row_ror:2 row_mask:0xf bank_mask:0xf
	v_mov_b32_dpp v45, v47 row_ror:1 row_mask:0xf bank_mask:0xf
	v_mov_b32_dpp v53, v47 row_ror:2 row_mask:0xf bank_mask:0xf
	v_mov_b32_e32 v153, v152
	v_mov_b32_dpp v46, v40 row_ror:1 row_mask:0xf bank_mask:0xf
	v_mov_b32_dpp v54, v40 row_ror:2 row_mask:0xf bank_mask:0xf
	v_mov_b32_dpp v47, v41 row_ror:1 row_mask:0xf bank_mask:0xf
	v_mov_b32_dpp v55, v41 row_ror:2 row_mask:0xf bank_mask:0xf
	v_mov_b32_dpp v40, v42 row_ror:1 row_mask:0xf bank_mask:0xf
	v_mov_b32_dpp v56, v42 row_ror:2 row_mask:0xf bank_mask:0xf
	v_mov_b32_dpp v41, v43 row_ror:1 row_mask:0xf bank_mask:0xf
	v_mov_b32_dpp v57, v43 row_ror:2 row_mask:0xf bank_mask:0xf
	v_pk_mul_f32 v[42:43], v[36:37], v[152:153]
	v_pk_mul_f32 v[58:59], v[32:33], v[152:153]
	s_nop 0
	v_mov_b32_dpp v48, v42 row_shr:1 row_mask:0xf bank_mask:0xf
	v_mov_b32_dpp v50, v42 row_shr:2 row_mask:0xf bank_mask:0xf
	v_mov_b32_dpp v49, v43 row_shr:1 row_mask:0xf bank_mask:0xf
	v_mov_b32_dpp v51, v43 row_shr:2 row_mask:0xf bank_mask:0xf
	v_pk_fma_f32 v[42:43], v[42:43], v[72:73], v[76:77]
	v_mov_b32_dpp v46, v58 row_shr:1 row_mask:0xf bank_mask:0xf
	v_pk_fma_f32 v[42:43], v[68:69], v[48:49], v[42:43]
	v_mov_b32_dpp v47, v59 row_shr:1 row_mask:0xf bank_mask:0xf
	v_pk_fma_f32 v[42:43], v[64:65], v[50:51], v[42:43]
	v_pk_fma_f32 v[50:51], v[58:59], v[88:89], v[92:93]
	v_mul_f32_e32 v48, 0xbfb8aa3b, v42
	v_mul_f32_e32 v49, 0xbfb8aa3b, v43
	v_exp_f32_e32 v48, v48
	v_exp_f32_e32 v49, v49
	v_mov_b32_dpp v54, v58 row_shr:2 row_mask:0xf bank_mask:0xf
	v_mov_b32_dpp v55, v59 row_shr:2 row_mask:0xf bank_mask:0xf
	v_add_f32_e32 v48, 1.0, v48
	v_add_f32_e32 v49, 1.0, v49
	v_rcp_f32_e32 v48, v48
	v_rcp_f32_e32 v49, v49
	v_pk_fma_f32 v[46:47], v[84:85], v[46:47], v[50:51]
	v_pk_mul_f32 v[42:43], v[42:43], v[48:49]
	v_pk_fma_f32 v[46:47], v[80:81], v[54:55], v[46:47]
	v_pk_mul_f32 v[48:49], v[34:35], v[152:153]
	v_pk_mul_f32 v[42:43], v[42:43], v[46:47]
	v_pk_mul_f32 v[46:47], v[38:39], v[152:153]
	v_mov_b32_dpp v40, v48 row_shr:1 row_mask:0xf bank_mask:0xf
	v_mov_b32_dpp v56, v48 row_shr:2 row_mask:0xf bank_mask:0xf
	v_mov_b32_dpp v44, v46 row_shr:1 row_mask:0xf bank_mask:0xf
	v_mov_b32_dpp v52, v46 row_shr:2 row_mask:0xf bank_mask:0xf
	v_mov_b32_dpp v45, v47 row_shr:1 row_mask:0xf bank_mask:0xf
	v_mov_b32_dpp v53, v47 row_shr:2 row_mask:0xf bank_mask:0xf
	v_pk_fma_f32 v[46:47], v[46:47], v[74:75], v[78:79]
	v_mov_b32_dpp v41, v49 row_shr:1 row_mask:0xf bank_mask:0xf
	v_pk_fma_f32 v[44:45], v[70:71], v[44:45], v[46:47]
	v_mov_b32_dpp v57, v49 row_shr:2 row_mask:0xf bank_mask:0xf
	v_pk_fma_f32 v[44:45], v[66:67], v[52:53], v[44:45]
	v_pk_fma_f32 v[48:49], v[48:49], v[90:91], v[94:95]
	v_mul_f32_e32 v46, 0xbfb8aa3b, v44
	v_mul_f32_e32 v47, 0xbfb8aa3b, v45
	v_exp_f32_e32 v46, v46
	v_exp_f32_e32 v47, v47
	v_pk_fma_f32 v[40:41], v[86:87], v[40:41], v[48:49]
	v_cvt_pk_bf16_f32 v42, v42, v43
	v_add_f32_e32 v46, 1.0, v46
	v_add_f32_e32 v47, 1.0, v47
	v_rcp_f32_e32 v46, v46
	v_rcp_f32_e32 v47, v47
	v_pk_fma_f32 v[40:41], v[82:83], v[56:57], v[40:41]
	v_pk_mul_f32 v[44:45], v[44:45], v[46:47]
	s_nop 0
	v_pk_mul_f32 v[40:41], v[44:45], v[40:41]
	s_nop 0
	v_cvt_pk_bf16_f32 v43, v40, v41
	global_store_dwordx2 v[142:143], v[42:43], off offset:32
	s_and_saveexec_b64 s[2:3], s[42:43]
	s_cbranch_execz .LBB0_1628
	v_lshl_add_u64 v[40:41], s[12:13], 0, v[154:155]
	v_lshl_add_u64 v[40:41], v[106:107], 2, v[40:41]
	v_pk_mul_f32 v[38:39], v[38:39], v[152:153] op_sel_hi:[1,0]
	v_pk_mul_f32 v[36:37], v[36:37], v[152:153] op_sel_hi:[1,0]
	global_store_dwordx4 v[40:41], v[36:39], off
	v_pk_mul_f32 v[34:35], v[34:35], v[152:153] op_sel_hi:[1,0]
	v_pk_mul_f32 v[32:33], v[32:33], v[152:153] op_sel_hi:[1,0]
	v_add_co_u32_e32 v36, vcc, 0x2000, v40
	s_nop 1
	v_addc_co_u32_e32 v37, vcc, 0, v41, vcc
	global_store_dwordx4 v[36:37], v[32:35], off offset:3072
.LBB0_1628:
	s_or_b64 exec, exec, s[2:3]
	v_mov_b32_e32 v103, v102
	v_pk_mul_f32 v[32:33], v[28:29], v[102:103]
	v_pk_mul_f32 v[34:35], v[24:25], v[102:103]
	v_pk_mul_f32 v[36:37], v[30:31], v[102:103]
	v_pk_mul_f32 v[38:39], v[26:27], v[102:103]
	v_mov_b32_dpp v40, v32 row_ror:1 row_mask:0xf bank_mask:0xf
	v_mov_b32_dpp v42, v32 row_ror:2 row_mask:0xf bank_mask:0xf
	v_mov_b32_dpp v41, v33 row_ror:1 row_mask:0xf bank_mask:0xf
	v_mov_b32_dpp v43, v33 row_ror:2 row_mask:0xf bank_mask:0xf
	v_mov_b32_dpp v44, v34 row_ror:1 row_mask:0xf bank_mask:0xf
	v_mov_b32_dpp v46, v34 row_ror:2 row_mask:0xf bank_mask:0xf
	v_mov_b32_dpp v45, v35 row_ror:1 row_mask:0xf bank_mask:0xf
	v_mov_b32_dpp v47, v35 row_ror:2 row_mask:0xf bank_mask:0xf
	v_mov_b32_dpp v48, v36 row_ror:1 row_mask:0xf bank_mask:0xf
	v_mov_b32_dpp v50, v36 row_ror:2 row_mask:0xf bank_mask:0xf
	v_mov_b32_dpp v49, v37 row_ror:1 row_mask:0xf bank_mask:0xf
	v_mov_b32_dpp v51, v37 row_ror:2 row_mask:0xf bank_mask:0xf
	v_mov_b32_dpp v52, v38 row_ror:1 row_mask:0xf bank_mask:0xf
	v_mov_b32_dpp v54, v38 row_ror:2 row_mask:0xf bank_mask:0xf
	v_mov_b32_dpp v53, v39 row_ror:1 row_mask:0xf bank_mask:0xf
	v_mov_b32_dpp v55, v39 row_ror:2 row_mask:0xf bank_mask:0xf
	v_mov_b32_dpp v40, v32 row_shr:1 row_mask:0xf bank_mask:0xf
	v_mov_b32_dpp v42, v32 row_shr:2 row_mask:0xf bank_mask:0xf
	v_mov_b32_dpp v41, v33 row_shr:1 row_mask:0xf bank_mask:0xf
	v_mov_b32_dpp v43, v33 row_shr:2 row_mask:0xf bank_mask:0xf
	v_mov_b32_dpp v44, v34 row_shr:1 row_mask:0xf bank_mask:0xf
	v_mov_b32_dpp v46, v34 row_shr:2 row_mask:0xf bank_mask:0xf
	v_mov_b32_dpp v45, v35 row_shr:1 row_mask:0xf bank_mask:0xf
	v_mov_b32_dpp v47, v35 row_shr:2 row_mask:0xf bank_mask:0xf
	v_mov_b32_dpp v48, v36 row_shr:1 row_mask:0xf bank_mask:0xf
	v_mov_b32_dpp v50, v36 row_shr:2 row_mask:0xf bank_mask:0xf
	v_mov_b32_dpp v49, v37 row_shr:1 row_mask:0xf bank_mask:0xf
	v_mov_b32_dpp v51, v37 row_shr:2 row_mask:0xf bank_mask:0xf
	v_mov_b32_dpp v52, v38 row_shr:1 row_mask:0xf bank_mask:0xf
	v_mov_b32_dpp v54, v38 row_shr:2 row_mask:0xf bank_mask:0xf
	v_mov_b32_dpp v53, v39 row_shr:1 row_mask:0xf bank_mask:0xf
	v_mov_b32_dpp v55, v39 row_shr:2 row_mask:0xf bank_mask:0xf
	s_and_saveexec_b64 s[2:3], s[44:45]
	s_cbranch_execz .LBB0_1630
	v_pk_fma_f32 v[56:57], v[32:33], v[72:73], v[76:77]
	v_readlane_b32 s44, v249, 58
	v_pk_fma_f32 v[40:41], v[68:69], v[40:41], v[56:57]
	v_pk_fma_f32 v[56:57], v[34:35], v[88:89], v[92:93]
	v_pk_fma_f32 v[40:41], v[64:65], v[42:43], v[40:41]
	v_pk_fma_f32 v[44:45], v[84:85], v[44:45], v[56:57]
	v_mul_f32_e32 v42, 0xbfb8aa3b, v40
	v_mul_f32_e32 v43, 0xbfb8aa3b, v41
	v_exp_f32_e32 v42, v42
	v_exp_f32_e32 v43, v43
	v_pk_fma_f32 v[44:45], v[80:81], v[46:47], v[44:45]
	v_readlane_b32 s45, v249, 59
	v_add_f32_e32 v42, 1.0, v42
	v_add_f32_e32 v43, 1.0, v43
	v_rcp_f32_e32 v42, v42
	v_rcp_f32_e32 v43, v43
	s_nop 0
	v_pk_mul_f32 v[40:41], v[40:41], v[42:43]
	v_pk_fma_f32 v[42:43], v[36:37], v[74:75], v[78:79]
	v_pk_mul_f32 v[40:41], v[40:41], v[44:45]
	v_pk_fma_f32 v[42:43], v[70:71], v[48:49], v[42:43]
	v_cvt_pk_bf16_f32 v40, v40, v41
	v_pk_fma_f32 v[42:43], v[66:67], v[50:51], v[42:43]
	s_nop 0
	v_mul_f32_e32 v46, 0xbfb8aa3b, v42
	v_mul_f32_e32 v47, 0xbfb8aa3b, v43
	v_exp_f32_e32 v46, v46
	v_exp_f32_e32 v47, v47
	v_add_f32_e32 v44, 1.0, v46
	v_add_f32_e32 v45, 1.0, v47
	v_rcp_f32_e32 v44, v44
	v_rcp_f32_e32 v45, v45
	v_pk_fma_f32 v[46:47], v[38:39], v[90:91], v[94:95]
	v_pk_mul_f32 v[42:43], v[42:43], v[44:45]
	v_pk_fma_f32 v[46:47], v[86:87], v[52:53], v[46:47]
	s_nop 0
	v_pk_fma_f32 v[46:47], v[82:83], v[54:55], v[46:47]
	s_nop 0
	v_pk_mul_f32 v[42:43], v[42:43], v[46:47]
	s_nop 0
	v_cvt_pk_bf16_f32 v41, v42, v43
	v_mov_b64_e32 v[42:43], s[44:45]
	v_mad_i64_i32 v[42:43], s[44:45], v171, s19, v[42:43]
	v_lshl_add_u64 v[42:43], v[106:107], 1, v[42:43]
	global_store_dwordx2 v[42:43], v[40:41], off

.LBB0_1632:
	s_or_b64 exec, exec, s[2:3]
	s_nop 0
	v_mov_b32_e32 v137, v136
	v_mov_b32_dpp v24, v32 row_ror:1 row_mask:0xf bank_mask:0xf
	v_mov_b32_dpp v26, v32 row_ror:2 row_mask:0xf bank_mask:0xf
	v_mov_b32_dpp v25, v33 row_ror:1 row_mask:0xf bank_mask:0xf
	v_mov_b32_dpp v27, v33 row_ror:2 row_mask:0xf bank_mask:0xf
	v_mov_b32_dpp v28, v36 row_ror:1 row_mask:0xf bank_mask:0xf
	v_mov_b32_dpp v30, v36 row_ror:2 row_mask:0xf bank_mask:0xf
	v_mov_b32_dpp v29, v37 row_ror:1 row_mask:0xf bank_mask:0xf
	v_mov_b32_dpp v31, v37 row_ror:2 row_mask:0xf bank_mask:0xf
	v_mov_b32_dpp v32, v34 row_ror:1 row_mask:0xf bank_mask:0xf
	v_mov_b32_dpp v36, v34 row_ror:2 row_mask:0xf bank_mask:0xf
	v_mov_b32_dpp v33, v35 row_ror:1 row_mask:0xf bank_mask:0xf
	v_mov_b32_dpp v37, v35 row_ror:2 row_mask:0xf bank_mask:0xf
	v_pk_mul_f32 v[20:21], v[20:21], v[136:137]
	v_mov_b32_dpp v34, v38 row_ror:1 row_mask:0xf bank_mask:0xf
	v_mov_b32_dpp v40, v38 row_ror:2 row_mask:0xf bank_mask:0xf
	v_mov_b32_dpp v35, v39 row_ror:1 row_mask:0xf bank_mask:0xf
	v_mov_b32_dpp v41, v39 row_ror:2 row_mask:0xf bank_mask:0xf
	v_mov_b32_dpp v24, v20 row_shr:1 row_mask:0xf bank_mask:0xf
	v_mov_b32_dpp v25, v21 row_shr:1 row_mask:0xf bank_mask:0xf
	v_pk_fma_f32 v[38:39], v[20:21], v[72:73], v[76:77]
	v_mov_b32_dpp v26, v20 row_shr:2 row_mask:0xf bank_mask:0xf
	v_mov_b32_dpp v27, v21 row_shr:2 row_mask:0xf bank_mask:0xf
	v_pk_fma_f32 v[24:25], v[68:69], v[24:25], v[38:39]
	v_pk_mul_f32 v[22:23], v[22:23], v[136:137]
	v_pk_fma_f32 v[24:25], v[64:65], v[26:27], v[24:25]
	v_pk_mul_f32 v[16:17], v[16:17], v[136:137]
	v_mul_f32_e32 v26, 0xbfb8aa3b, v24
	v_mul_f32_e32 v27, 0xbfb8aa3b, v25
	v_exp_f32_e32 v26, v26
	v_exp_f32_e32 v27, v27
	v_mov_b32_dpp v28, v22 row_shr:1 row_mask:0xf bank_mask:0xf
	v_mov_b32_dpp v29, v23 row_shr:1 row_mask:0xf bank_mask:0xf
	v_add_f32_e32 v26, 1.0, v26
	v_add_f32_e32 v27, 1.0, v27
	v_rcp_f32_e32 v26, v26
	v_rcp_f32_e32 v27, v27
	v_mov_b32_dpp v30, v22 row_shr:2 row_mask:0xf bank_mask:0xf
	v_mov_b32_dpp v31, v23 row_shr:2 row_mask:0xf bank_mask:0xf
	v_pk_mul_f32 v[18:19], v[18:19], v[136:137]
	v_pk_mul_f32 v[24:25], v[24:25], v[26:27]
	v_pk_fma_f32 v[26:27], v[22:23], v[74:75], v[78:79]
	v_mov_b32_dpp v32, v16 row_shr:1 row_mask:0xf bank_mask:0xf
	v_pk_fma_f32 v[26:27], v[70:71], v[28:29], v[26:27]
	v_mov_b32_dpp v33, v17 row_shr:1 row_mask:0xf bank_mask:0xf
	v_pk_fma_f32 v[26:27], v[66:67], v[30:31], v[26:27]
	v_pk_fma_f32 v[38:39], v[16:17], v[88:89], v[92:93]
	v_mul_f32_e32 v28, 0xbfb8aa3b, v26
	v_mul_f32_e32 v29, 0xbfb8aa3b, v27
	v_exp_f32_e32 v28, v28
	v_exp_f32_e32 v29, v29
	v_mov_b32_dpp v34, v18 row_shr:1 row_mask:0xf bank_mask:0xf
	v_mov_b32_dpp v35, v19 row_shr:1 row_mask:0xf bank_mask:0xf
	v_add_f32_e32 v28, 1.0, v28
	v_add_f32_e32 v29, 1.0, v29
	v_rcp_f32_e32 v28, v28
	v_rcp_f32_e32 v29, v29
	v_pk_fma_f32 v[30:31], v[18:19], v[90:91], v[94:95]
	v_mov_b32_dpp v36, v16 row_shr:2 row_mask:0xf bank_mask:0xf
	v_mov_b32_dpp v37, v17 row_shr:2 row_mask:0xf bank_mask:0xf
	v_pk_fma_f32 v[32:33], v[84:85], v[32:33], v[38:39]
	v_mov_b32_dpp v40, v18 row_shr:2 row_mask:0xf bank_mask:0xf
	v_mov_b32_dpp v41, v19 row_shr:2 row_mask:0xf bank_mask:0xf
	v_pk_fma_f32 v[30:31], v[86:87], v[34:35], v[30:31]
	v_pk_fma_f32 v[32:33], v[80:81], v[36:37], v[32:33]
	v_pk_fma_f32 v[30:31], v[82:83], v[40:41], v[30:31]
	v_pk_mul_f32 v[26:27], v[26:27], v[28:29]
	v_pk_mul_f32 v[24:25], v[24:25], v[32:33]
	v_pk_mul_f32 v[26:27], v[26:27], v[30:31]
	v_cvt_pk_bf16_f32 v24, v24, v25
	v_cvt_pk_bf16_f32 v25, v26, v27
	global_store_dwordx2 v[146:147], v[24:25], off offset:32
	v_mov_b32_dpp v24, v20 row_ror:1 row_mask:0xf bank_mask:0xf
	v_mov_b32_dpp v26, v20 row_ror:2 row_mask:0xf bank_mask:0xf
	v_mov_b32_dpp v25, v21 row_ror:1 row_mask:0xf bank_mask:0xf
	v_mov_b32_dpp v27, v21 row_ror:2 row_mask:0xf bank_mask:0xf
	v_mov_b32_e32 v101, v100
	v_mov_b32_dpp v20, v22 row_ror:1 row_mask:0xf bank_mask:0xf
	v_mov_b32_dpp v28, v22 row_ror:2 row_mask:0xf bank_mask:0xf
	v_mov_b32_dpp v21, v23 row_ror:1 row_mask:0xf bank_mask:0xf
	v_mov_b32_dpp v29, v23 row_ror:2 row_mask:0xf bank_mask:0xf
	v_mov_b32_dpp v22, v16 row_ror:1 row_mask:0xf bank_mask:0xf
	v_mov_b32_dpp v30, v16 row_ror:2 row_mask:0xf bank_mask:0xf
	v_mov_b32_dpp v23, v17 row_ror:1 row_mask:0xf bank_mask:0xf
	v_mov_b32_dpp v31, v17 row_ror:2 row_mask:0xf bank_mask:0xf
	v_pk_mul_f32 v[12:13], v[12:13], v[100:101]
	v_mov_b32_dpp v16, v18 row_ror:1 row_mask:0xf bank_mask:0xf
	v_mov_b32_dpp v32, v18 row_ror:2 row_mask:0xf bank_mask:0xf
	v_mov_b32_dpp v17, v19 row_ror:1 row_mask:0xf bank_mask:0xf
	v_mov_b32_dpp v33, v19 row_ror:2 row_mask:0xf bank_mask:0xf
	v_mov_b32_dpp v24, v12 row_shr:1 row_mask:0xf bank_mask:0xf
	v_mov_b32_dpp v25, v13 row_shr:1 row_mask:0xf bank_mask:0xf
	v_pk_fma_f32 v[18:19], v[12:13], v[72:73], v[76:77]
	v_mov_b32_dpp v26, v12 row_shr:2 row_mask:0xf bank_mask:0xf
	v_mov_b32_dpp v27, v13 row_shr:2 row_mask:0xf bank_mask:0xf
	v_pk_fma_f32 v[18:19], v[68:69], v[24:25], v[18:19]
	v_pk_mul_f32 v[8:9], v[8:9], v[100:101]
	v_pk_fma_f32 v[18:19], v[64:65], v[26:27], v[18:19]
	v_pk_fma_f32 v[26:27], v[8:9], v[88:89], v[92:93]
	v_mul_f32_e32 v24, 0xbfb8aa3b, v18
	v_mul_f32_e32 v25, 0xbfb8aa3b, v19
	v_exp_f32_e32 v24, v24
	v_exp_f32_e32 v25, v25
	v_mov_b32_dpp v22, v8 row_shr:1 row_mask:0xf bank_mask:0xf
	v_mov_b32_dpp v23, v9 row_shr:1 row_mask:0xf bank_mask:0xf
	v_add_f32_e32 v24, 1.0, v24
	v_add_f32_e32 v25, 1.0, v25
	v_rcp_f32_e32 v24, v24
	v_rcp_f32_e32 v25, v25
	v_mov_b32_dpp v30, v8 row_shr:2 row_mask:0xf bank_mask:0xf
	v_mov_b32_dpp v31, v9 row_shr:2 row_mask:0xf bank_mask:0xf
	v_pk_fma_f32 v[22:23], v[84:85], v[22:23], v[26:27]
	v_pk_mul_f32 v[18:19], v[18:19], v[24:25]
	v_pk_fma_f32 v[22:23], v[80:81], v[30:31], v[22:23]
	v_pk_mul_f32 v[14:15], v[14:15], v[100:101]
	v_pk_mul_f32 v[18:19], v[18:19], v[22:23]
	v_pk_fma_f32 v[22:23], v[14:15], v[74:75], v[78:79]
	v_mov_b32_dpp v20, v14 row_shr:1 row_mask:0xf bank_mask:0xf
	v_mov_b32_dpp v21, v15 row_shr:1 row_mask:0xf bank_mask:0xf
	v_mov_b32_dpp v28, v14 row_shr:2 row_mask:0xf bank_mask:0xf
	v_mov_b32_dpp v29, v15 row_shr:2 row_mask:0xf bank_mask:0xf
	v_pk_fma_f32 v[20:21], v[70:71], v[20:21], v[22:23]
	v_pk_mul_f32 v[10:11], v[10:11], v[100:101]
	v_pk_fma_f32 v[20:21], v[66:67], v[28:29], v[20:21]
	v_pk_fma_f32 v[24:25], v[10:11], v[90:91], v[94:95]
	v_mul_f32_e32 v22, 0xbfb8aa3b, v20
	v_mul_f32_e32 v23, 0xbfb8aa3b, v21
	v_exp_f32_e32 v22, v22
	v_exp_f32_e32 v23, v23
	v_mov_b32_dpp v16, v10 row_shr:1 row_mask:0xf bank_mask:0xf
	v_mov_b32_dpp v17, v11 row_shr:1 row_mask:0xf bank_mask:0xf
	v_add_f32_e32 v22, 1.0, v22
	v_add_f32_e32 v23, 1.0, v23
	v_rcp_f32_e32 v22, v22
	v_rcp_f32_e32 v23, v23
	v_mov_b32_dpp v32, v10 row_shr:2 row_mask:0xf bank_mask:0xf
	v_mov_b32_dpp v33, v11 row_shr:2 row_mask:0xf bank_mask:0xf
	v_pk_fma_f32 v[16:17], v[86:87], v[16:17], v[24:25]
	v_pk_mul_f32 v[20:21], v[20:21], v[22:23]
	v_pk_fma_f32 v[16:17], v[82:83], v[32:33], v[16:17]
	v_cvt_pk_bf16_f32 v18, v18, v19
	v_pk_mul_f32 v[16:17], v[20:21], v[16:17]
	v_cvt_pk_bf16_f32 v19, v16, v17
	global_store_dwordx2 v[148:149], v[18:19], off offset:32
	v_mov_b32_dpp v16, v12 row_ror:1 row_mask:0xf bank_mask:0xf
	v_mov_b32_dpp v18, v12 row_ror:2 row_mask:0xf bank_mask:0xf
	v_mov_b32_dpp v17, v13 row_ror:1 row_mask:0xf bank_mask:0xf
	v_mov_b32_dpp v19, v13 row_ror:2 row_mask:0xf bank_mask:0xf
	v_mov_b32_dpp v12, v14 row_ror:1 row_mask:0xf bank_mask:0xf
	v_mov_b32_dpp v20, v14 row_ror:2 row_mask:0xf bank_mask:0xf
	v_mov_b32_dpp v13, v15 row_ror:1 row_mask:0xf bank_mask:0xf
	v_mov_b32_dpp v21, v15 row_ror:2 row_mask:0xf bank_mask:0xf
	v_mov_b32_e32 v99, v98
	v_mov_b32_dpp v14, v8 row_ror:1 row_mask:0xf bank_mask:0xf
	v_mov_b32_dpp v22, v8 row_ror:2 row_mask:0xf bank_mask:0xf
	v_mov_b32_dpp v15, v9 row_ror:1 row_mask:0xf bank_mask:0xf
	v_mov_b32_dpp v23, v9 row_ror:2 row_mask:0xf bank_mask:0xf
	v_mov_b32_dpp v8, v10 row_ror:1 row_mask:0xf bank_mask:0xf
	v_mov_b32_dpp v24, v10 row_ror:2 row_mask:0xf bank_mask:0xf
	v_mov_b32_dpp v9, v11 row_ror:1 row_mask:0xf bank_mask:0xf
	v_mov_b32_dpp v25, v11 row_ror:2 row_mask:0xf bank_mask:0xf
	v_pk_mul_f32 v[10:11], v[4:5], v[98:99]
	v_pk_mul_f32 v[26:27], v[0:1], v[98:99]
	s_nop 0
	v_mov_b32_dpp v16, v10 row_shr:1 row_mask:0xf bank_mask:0xf
	v_mov_b32_dpp v18, v10 row_shr:2 row_mask:0xf bank_mask:0xf
	v_mov_b32_dpp v17, v11 row_shr:1 row_mask:0xf bank_mask:0xf
	v_mov_b32_dpp v19, v11 row_shr:2 row_mask:0xf bank_mask:0xf
	v_pk_fma_f32 v[10:11], v[10:11], v[72:73], v[76:77]
	v_mov_b32_dpp v14, v26 row_shr:1 row_mask:0xf bank_mask:0xf
	v_pk_fma_f32 v[10:11], v[68:69], v[16:17], v[10:11]
	v_mov_b32_dpp v15, v27 row_shr:1 row_mask:0xf bank_mask:0xf
	v_pk_fma_f32 v[10:11], v[64:65], v[18:19], v[10:11]
	v_pk_fma_f32 v[18:19], v[26:27], v[88:89], v[92:93]
	v_mul_f32_e32 v16, 0xbfb8aa3b, v10
	v_mul_f32_e32 v17, 0xbfb8aa3b, v11
	v_exp_f32_e32 v16, v16
	v_exp_f32_e32 v17, v17
	v_mov_b32_dpp v22, v26 row_shr:2 row_mask:0xf bank_mask:0xf
	v_mov_b32_dpp v23, v27 row_shr:2 row_mask:0xf bank_mask:0xf
	v_add_f32_e32 v16, 1.0, v16
	v_add_f32_e32 v17, 1.0, v17
	v_rcp_f32_e32 v16, v16
	v_rcp_f32_e32 v17, v17
	v_pk_fma_f32 v[14:15], v[84:85], v[14:15], v[18:19]
	v_pk_mul_f32 v[10:11], v[10:11], v[16:17]
	v_pk_fma_f32 v[14:15], v[80:81], v[22:23], v[14:15]
	v_pk_mul_f32 v[16:17], v[2:3], v[98:99]
	v_pk_mul_f32 v[10:11], v[10:11], v[14:15]
	v_pk_mul_f32 v[14:15], v[6:7], v[98:99]
	v_mov_b32_dpp v8, v16 row_shr:1 row_mask:0xf bank_mask:0xf
	v_mov_b32_dpp v24, v16 row_shr:2 row_mask:0xf bank_mask:0xf
	v_mov_b32_dpp v12, v14 row_shr:1 row_mask:0xf bank_mask:0xf
	v_mov_b32_dpp v20, v14 row_shr:2 row_mask:0xf bank_mask:0xf
	v_mov_b32_dpp v13, v15 row_shr:1 row_mask:0xf bank_mask:0xf
	v_mov_b32_dpp v21, v15 row_shr:2 row_mask:0xf bank_mask:0xf
	v_pk_fma_f32 v[14:15], v[14:15], v[74:75], v[78:79]
	v_mov_b32_dpp v9, v17 row_shr:1 row_mask:0xf bank_mask:0xf
	v_pk_fma_f32 v[12:13], v[70:71], v[12:13], v[14:15]
	v_mov_b32_dpp v25, v17 row_shr:2 row_mask:0xf bank_mask:0xf
	v_pk_fma_f32 v[12:13], v[66:67], v[20:21], v[12:13]
	v_pk_fma_f32 v[16:17], v[16:17], v[90:91], v[94:95]
	v_mul_f32_e32 v14, 0xbfb8aa3b, v12
	v_mul_f32_e32 v15, 0xbfb8aa3b, v13
	v_exp_f32_e32 v14, v14
	v_exp_f32_e32 v15, v15
	v_pk_fma_f32 v[8:9], v[86:87], v[8:9], v[16:17]
	v_cvt_pk_bf16_f32 v10, v10, v11
	v_add_f32_e32 v14, 1.0, v14
	v_add_f32_e32 v15, 1.0, v15
	v_rcp_f32_e32 v14, v14
	v_rcp_f32_e32 v15, v15
	v_pk_fma_f32 v[8:9], v[82:83], v[24:25], v[8:9]
	v_pk_mul_f32 v[12:13], v[12:13], v[14:15]
	s_nop 0
	v_pk_mul_f32 v[8:9], v[12:13], v[8:9]
	s_nop 0
	v_cvt_pk_bf16_f32 v11, v8, v9
	global_store_dwordx2 v[104:105], v[10:11], off offset:32
	s_and_saveexec_b64 s[2:3], s[42:43]
	s_cbranch_execz .LBB0_1601
	v_lshl_add_u64 v[8:9], s[12:13], 0, v[96:97]
	v_lshl_add_u64 v[8:9], v[106:107], 2, v[8:9]
	v_pk_mul_f32 v[6:7], v[6:7], v[98:99] op_sel_hi:[1,0]
	v_pk_mul_f32 v[4:5], v[4:5], v[98:99] op_sel_hi:[1,0]
	global_store_dwordx4 v[8:9], v[4:7], off
	v_pk_mul_f32 v[2:3], v[2:3], v[98:99] op_sel_hi:[1,0]
	v_pk_mul_f32 v[0:1], v[0:1], v[98:99] op_sel_hi:[1,0]
	v_add_co_u32_e32 v4, vcc, 0x2000, v8
	s_nop 1
	v_addc_co_u32_e32 v5, vcc, 0, v9, vcc
	global_store_dwordx4 v[4:5], v[0:3], off offset:3072
	s_branch .LBB0_1601
